# v42 + merge(helper)/P4: sc1 only on the A-operand LDS-DMA loads, per-unit acquire invalidate dropped (weights stay L2-cached)
# speedup vs baseline: 1.0114x; 1.0114x over previous
.LBB0_1228:
	s_or_b64 exec, exec, s[10:11]
	s_waitcnt lgkmcnt(0)
	s_barrier
	ds_read_b32 v0, v140
	s_mov_b64 s[10:11], -1
	s_waitcnt lgkmcnt(0)
	v_readfirstlane_b32 s14, v0
	ds_read_b32 v1, v140 offset:8
	s_waitcnt lgkmcnt(0)
	v_readfirstlane_b32 s12, v1
	s_nop 1
	s_cmp_eq_u32 s12, 1
	s_cbranch_scc1 .Lp4_oneshot
	s_cmpk_gt_u32 s14, 0x1ff
	s_cbranch_scc1 .LBB0_1200
	v_mbcnt_lo_u32_b32 v2, -1, 0
	v_mbcnt_hi_u32_b32 v2, -1, v2
	s_lshl_b32 s4, s14, 2
	v_lshl_or_b32 v4, v2, 4, s66
	v_ashrrev_i32_e32 v0, 31, v4
	v_lshrrev_b32_e32 v0, 22, v0
	v_add_u32_e32 v0, v4, v0
	v_ashrrev_i32_e32 v0, 10, v0
	v_mul_i32_i24_e32 v1, 0x400, v0
	v_sub_u32_e32 v1, v4, v1
	v_lshrrev_b32_e32 v3, 4, v1
	v_bitop3_b32 v3, v3, v1, 32 bitop3:0x6c
	v_lshlrev_b32_e32 v1, 3, v0
	v_and_b32_e32 v5, -16, v1
	v_ashrrev_i32_e32 v1, 31, v3
	v_lshrrev_b32_e32 v1, 26, v1
	v_add_u32_e32 v6, v3, v1
	v_ashrrev_i32_e32 v1, 6, v6
	v_and_b32_e32 v6, 0xc0, v6
	v_sub_u32_e32 v3, v3, v6
	v_lshlrev_b32_e32 v7, 5, v0
	v_ashrrev_i16_sdwa v3, v141, sext(v3) dst_sel:DWORD dst_unused:UNUSED_PAD src0_sel:DWORD src1_sel:BYTE_0
	v_and_b32_e32 v7, 32, v7
	v_bfe_i32 v3, v3, 0, 16
	v_add_u32_e32 v5, v1, v5
	v_and_b32_e32 v9, 3, v1
	v_add_lshl_u32 v7, v7, v3, 1
	v_lshlrev_b32_e32 v6, 1, v5
	v_lshrrev_b32_e32 v8, 2, v5
	v_and_or_b32 v9, v5, s49, v9
	v_lshl_add_u32 v130, v5, 11, v7
	v_add_u32_e32 v5, 0x2000, v4
	v_ashrrev_i32_e32 v4, 31, v5
	v_lshrrev_b32_e32 v4, 22, v4
	v_and_b32_e32 v6, 24, v6
	v_and_b32_e32 v8, 4, v8
	v_add_u32_e32 v4, v5, v4
	v_or3_b32 v6, v9, v8, v6
	v_ashrrev_i32_e32 v4, 10, v4
	v_lshl_add_u32 v128, v6, 11, v7
	v_mul_i32_i24_e32 v6, 0x400, v4
	v_sub_u32_e32 v5, v5, v6
	v_lshrrev_b32_e32 v6, 4, v5
	v_bitop3_b32 v6, v6, v5, 32 bitop3:0x6c
	v_lshlrev_b32_e32 v5, 3, v4
	v_and_b32_e32 v7, -16, v5
	v_ashrrev_i32_e32 v5, 31, v6
	v_lshrrev_b32_e32 v5, 26, v5
	s_and_b32 s4, s4, 0x70
	s_lshr_b32 s15, s14, 5
	v_add_u32_e32 v8, v6, v5
	s_or_b32 s4, s4, s15
	v_ashrrev_i32_e32 v5, 6, v8
	v_and_b32_e32 v8, 0xffc0, v8
	s_and_b32 s20, s14, 3
	v_sub_u32_e32 v6, v6, v8
	s_lshl_b32 s21, s4, 19
	v_lshrrev_b16_e32 v8, 7, v6
	s_add_u32 s10, s64, s21
	v_and_b32_e32 v8, 1, v8
	s_addc_u32 s11, s65, 0
	s_lshl_b32 s16, s20, 19
	v_add_u32_e32 v7, v5, v7
	v_add_u16_e32 v6, v6, v8
	s_add_u32 s12, s50, s16
	v_lshlrev_b32_e32 v9, 5, v4
	v_ashrrev_i16_sdwa v6, v141, sext(v6) dst_sel:DWORD dst_unused:UNUSED_PAD src0_sel:DWORD src1_sel:BYTE_0
	v_lshlrev_b32_e32 v8, 1, v7
	v_lshrrev_b32_e32 v10, 2, v7
	v_and_b32_e32 v11, 3, v5
	s_addc_u32 s13, s51, 0
	s_add_i32 s30, s66, 0
	v_and_b32_e32 v9, 32, v9
	v_bfe_i32 v6, v6, 0, 16
	v_and_b32_e32 v8, 24, v8
	v_and_b32_e32 v10, 4, v10
	v_and_or_b32 v11, v7, s49, v11
	s_add_i32 m0, s30, 0x10000
	v_or3_b32 v8, v11, v10, v8
	v_add_lshl_u32 v9, v9, v6, 1
	global_load_lds_dwordx4 v128, s[12:13]
	s_add_i32 m0, s30, 0x12000
	v_lshl_add_u32 v134, v8, 11, v9
	s_add_u32 s18, s12, 0x40000
	global_load_lds_dwordx4 v134, s[12:13]
	s_addc_u32 s19, s13, 0
	s_add_i32 m0, s30, 0x14000
	s_add_i32 s31, s30, 0x2000
	global_load_lds_dwordx4 v128, s[18:19]
	s_add_i32 m0, s30, 0x16000
	v_lshl_add_u32 v132, v7, 11, v9
	global_load_lds_dwordx4 v134, s[18:19]
	s_mov_b32 m0, s30
	s_add_u32 s18, s10, 0x40000
	global_load_lds_dwordx4 v130, s[10:11] sc1
	s_mov_b32 m0, s31
	s_addc_u32 s19, s11, 0
	s_add_i32 s34, s30, 0x4000
	global_load_lds_dwordx4 v132, s[10:11] sc1
	s_mov_b32 m0, s34
	s_add_i32 s35, s30, 0x6000
	v_lshl_add_u64 v[8:9], s[12:13], 0, v[128:129]
	v_mov_b32_e32 v135, v129
	global_load_lds_dwordx4 v130, s[18:19] sc1
	s_mov_b32 m0, s35
	v_lshl_add_u64 v[10:11], s[12:13], 0, v[134:135]
	v_mov_b32_e32 v131, v129
	global_load_lds_dwordx4 v132, s[18:19] sc1
	v_lshl_add_u64 v[8:9], v[8:9], 0, s[6:7]
	s_add_i32 m0, s30, 0x18000
	v_lshl_add_u64 v[12:13], s[10:11], 0, v[130:131]
	v_mov_b32_e32 v133, v129
	global_load_lds_dwordx4 v[8:9], off
	v_lshl_add_u64 v[8:9], v[10:11], 0, s[6:7]
	s_add_i32 m0, s30, 0x1a000
	s_add_i32 s36, s30, 0x8000
	v_lshl_add_u64 v[14:15], s[10:11], 0, v[132:133]
	global_load_lds_dwordx4 v[8:9], off
	v_lshl_add_u64 v[8:9], v[12:13], 0, s[6:7]
	s_mov_b32 m0, s36
	s_add_i32 s37, s30, 0xa000
	global_load_lds_dwordx4 v[8:9], off sc1
	v_lshl_add_u64 v[8:9], v[14:15], 0, s[6:7]
	s_mov_b32 m0, s37
	s_add_u32 s18, s12, 0x40080
	global_load_lds_dwordx4 v[8:9], off sc1
	s_addc_u32 s19, s13, 0
	s_add_i32 m0, s30, 0x1c000
	s_and_b64 vcc, exec, s[0:1]
	global_load_lds_dwordx4 v128, s[18:19]
	s_add_i32 m0, s30, 0x1e000
	s_nop 0
	global_load_lds_dwordx4 v134, s[18:19]
	s_cbranch_vccnz .LBB0_1231
	s_barrier
.LBB0_1231:
	v_and_b32_e32 v142, 15, v2
	v_and_b32_e32 v143, 48, v2
	v_lshlrev_b32_e32 v2, 2, v2
	s_lshl_b32 s14, s14, 21
	v_lshl_or_b32 v7, v142, 6, v143
	v_and_b32_e32 v2, 32, v2
	s_and_b32 s14, s14, 0x3800000
	s_lshl_b32 s15, s15, 19
	v_bitop3_b32 v8, v7, s52, v2 bitop3:0xde
	v_bitop3_b32 v144, v7, s53, v2 bitop3:0xde
	s_add_i32 s14, s14, s15
	v_lshlrev_b32_e32 v2, 14, v0
	s_add_u32 s38, s76, s14
	v_and_b32_e32 v2, 0xffff8000, v2
	s_addc_u32 s39, s77, 0
	v_lshl_add_u32 v1, v1, 11, v2
	v_and_b32_e32 v0, 1, v0
	v_lshl_or_b32 v0, v0, 6, v1
	s_add_u32 s14, s3, s14
	v_lshl_add_u32 v0, v3, 1, v0
	v_mov_b32_e32 v1, v129
	s_addc_u32 s15, s28, 0
	v_lshl_add_u64 v[136:137], s[14:15], 0, v[0:1]
	v_lshlrev_b32_e32 v0, 14, v4
	v_and_b32_e32 v0, 0xffff8000, v0
	v_lshl_add_u32 v0, v5, 11, v0
	v_and_b32_e32 v1, 1, v4
	v_lshl_or_b32 v0, v1, 6, v0
	s_waitcnt vmcnt(8)
	s_barrier
	s_waitcnt vmcnt(6)
	v_lshl_add_u32 v0, v6, 1, v0
	v_mov_b32_e32 v1, v129
	v_lshl_add_u64 v[138:139], s[14:15], 0, v[0:1]
	s_add_u32 s40, s29, s16
	s_addc_u32 s41, s33, 0
	s_mov_b32 s42, -2
	s_mov_b64 s[14:15], 0
	v_add_u32_e32 v145, 0, v8
	s_barrier
	s_add_u32 s16, s38, s14
	s_addc_u32 s17, s39, s15
	s_add_u32 s16, s16, 0x13d00100
	s_addc_u32 s17, s17, 0
	s_add_u32 s43, s40, s14
	s_addc_u32 s44, s41, s15
	s_cmpk_eq_i32 s14, 0x700
	s_cselect_b32 s19, s11, s17
	s_cselect_b32 s18, s10, s16
	s_cselect_b32 s17, s13, s44
	s_cselect_b32 s16, s12, s43
	s_add_i32 s43, 0, 0x14000
	v_add_u32_e32 v158, s67, v144
	v_add_u32_e32 v174, s43, v144
	ds_read_b128 v[146:149], v158
	ds_read_b128 v[150:153], v158 offset:1024
	ds_read_b128 v[154:157], v158 offset:2048
	ds_read_b128 v[158:161], v158 offset:3072
	ds_read_b128 v[162:165], v174
	ds_read_b128 v[166:169], v174 offset:1024
	ds_read_b128 v[170:173], v174 offset:2048
	ds_read_b128 v[174:177], v174 offset:3072
	v_lshl_add_u64 v[210:211], v[136:137], 0, s[14:15]
	s_add_i32 m0, s30, 0xc000
	ds_read_b128 v[178:181], v145
	ds_read_b128 v[182:185], v145 offset:1024
	ds_read_b128 v[186:189], v145 offset:2048
	ds_read_b128 v[190:193], v145 offset:3072
	ds_read_b128 v[194:197], v145 offset:4096
	ds_read_b128 v[198:201], v145 offset:5120
	ds_read_b128 v[202:205], v145 offset:6144
	ds_read_b128 v[206:209], v145 offset:7168
	global_load_lds_dwordx4 v[210:211], off sc1
	v_lshl_add_u64 v[210:211], v[138:139], 0, s[14:15]
	s_add_i32 m0, s30, 0xe000
	s_nop 0
	global_load_lds_dwordx4 v[210:211], off sc1
	s_waitcnt vmcnt(8)
	s_waitcnt lgkmcnt(0)
	s_barrier
	s_waitcnt lgkmcnt(0)
	v_mfma_f32_16x16x32_f16 v[124:127], v[146:149], v[178:181], 0
	v_mfma_f32_16x16x32_f16 v[120:123], v[154:157], v[178:181], 0
	v_mfma_f32_16x16x32_f16 v[108:111], v[146:149], v[186:189], 0
	v_mfma_f32_16x16x32_f16 v[104:107], v[154:157], v[186:189], 0
	v_mfma_f32_16x16x32_f16 v[92:95], v[146:149], v[194:197], 0
	v_mfma_f32_16x16x32_f16 v[88:91], v[154:157], v[194:197], 0
	v_mfma_f32_16x16x32_f16 v[76:79], v[146:149], v[202:205], 0
	v_mfma_f32_16x16x32_f16 v[72:75], v[154:157], v[202:205], 0
	v_mfma_f32_16x16x32_f16 v[124:127], v[150:153], v[182:185], v[124:127]
	v_mfma_f32_16x16x32_f16 v[120:123], v[158:161], v[182:185], v[120:123]
	v_mfma_f32_16x16x32_f16 v[108:111], v[150:153], v[190:193], v[108:111]
	v_mfma_f32_16x16x32_f16 v[104:107], v[158:161], v[190:193], v[104:107]
	v_mfma_f32_16x16x32_f16 v[92:95], v[150:153], v[198:201], v[92:95]
	v_mfma_f32_16x16x32_f16 v[88:91], v[158:161], v[198:201], v[88:91]
	v_mfma_f32_16x16x32_f16 v[76:79], v[150:153], v[206:209], v[76:79]
	v_mfma_f32_16x16x32_f16 v[72:75], v[158:161], v[206:209], v[72:75]
	v_mfma_f32_16x16x32_f16 v[116:119], v[162:165], v[178:181], 0
	v_mfma_f32_16x16x32_f16 v[112:115], v[170:173], v[178:181], 0
	v_mfma_f32_16x16x32_f16 v[100:103], v[162:165], v[186:189], 0
	v_mfma_f32_16x16x32_f16 v[96:99], v[170:173], v[186:189], 0
	v_mfma_f32_16x16x32_f16 v[84:87], v[162:165], v[194:197], 0
	v_mfma_f32_16x16x32_f16 v[80:83], v[170:173], v[194:197], 0
	v_mfma_f32_16x16x32_f16 v[68:71], v[162:165], v[202:205], 0
	v_mfma_f32_16x16x32_f16 v[64:67], v[170:173], v[202:205], 0
	v_mfma_f32_16x16x32_f16 v[116:119], v[166:169], v[182:185], v[116:119]
	v_mfma_f32_16x16x32_f16 v[112:115], v[174:177], v[182:185], v[112:115]
	v_mfma_f32_16x16x32_f16 v[100:103], v[166:169], v[190:193], v[100:103]
	v_mfma_f32_16x16x32_f16 v[96:99], v[174:177], v[190:193], v[96:99]
	v_mfma_f32_16x16x32_f16 v[84:87], v[166:169], v[198:201], v[84:87]
	v_mfma_f32_16x16x32_f16 v[80:83], v[174:177], v[198:201], v[80:83]
	v_mfma_f32_16x16x32_f16 v[68:71], v[166:169], v[206:209], v[68:71]
	v_mfma_f32_16x16x32_f16 v[64:67], v[174:177], v[206:209], v[64:67]
	s_barrier
	s_add_i32 s44, s67, s66
	v_lshl_add_u64 v[210:211], s[16:17], 0, v[128:129]
	s_mov_b32 m0, s44
	ds_read_b128 v[178:181], v145 offset:16384
	ds_read_b128 v[182:185], v145 offset:17408
	ds_read_b128 v[186:189], v145 offset:18432
	ds_read_b128 v[190:193], v145 offset:19456
	ds_read_b128 v[194:197], v145 offset:20480
	ds_read_b128 v[198:201], v145 offset:21504
	ds_read_b128 v[202:205], v145 offset:22528
	ds_read_b128 v[206:209], v145 offset:23552
	global_load_lds_dwordx4 v[210:211], off
	s_add_i32 m0, s44, 0x2000
	s_add_u32 s44, s16, 0x40000
	v_lshl_add_u64 v[212:213], s[16:17], 0, v[134:135]
	s_addc_u32 s45, s17, 0
	s_add_i32 s43, s43, s66
	global_load_lds_dwordx4 v[212:213], off
	v_lshl_add_u64 v[214:215], s[44:45], 0, v[128:129]
	s_mov_b32 m0, s43
	v_lshl_add_u64 v[216:217], s[18:19], 0, v[132:133]
	global_load_lds_dwordx4 v[214:215], off
	v_lshl_add_u64 v[214:215], s[44:45], 0, v[134:135]
	s_add_i32 m0, s43, 0x2000
	s_nop 0
	global_load_lds_dwordx4 v[214:215], off
	v_lshl_add_u64 v[214:215], s[18:19], 0, v[130:131]
	s_mov_b32 m0, s30
	s_nop 0
	global_load_lds_dwordx4 v[214:215], off sc1
	s_mov_b32 m0, s31
	s_nop 0
	global_load_lds_dwordx4 v[216:217], off sc1
	s_waitcnt vmcnt(8)
	s_waitcnt lgkmcnt(0)
	s_barrier
	s_waitcnt lgkmcnt(0)
	v_mfma_f32_16x16x32_f16 v[60:63], v[146:149], v[178:181], 0
	v_mfma_f32_16x16x32_f16 v[56:59], v[154:157], v[178:181], 0
	v_mfma_f32_16x16x32_f16 v[44:47], v[146:149], v[186:189], 0
	v_mfma_f32_16x16x32_f16 v[40:43], v[154:157], v[186:189], 0
	v_mfma_f32_16x16x32_f16 v[28:31], v[146:149], v[194:197], 0
	v_mfma_f32_16x16x32_f16 v[24:27], v[154:157], v[194:197], 0
	v_mfma_f32_16x16x32_f16 v[12:15], v[146:149], v[202:205], 0
	v_mfma_f32_16x16x32_f16 v[8:11], v[154:157], v[202:205], 0
	v_mfma_f32_16x16x32_f16 v[60:63], v[150:153], v[182:185], v[60:63]
	v_mfma_f32_16x16x32_f16 v[56:59], v[158:161], v[182:185], v[56:59]
	v_mfma_f32_16x16x32_f16 v[44:47], v[150:153], v[190:193], v[44:47]
	v_mfma_f32_16x16x32_f16 v[40:43], v[158:161], v[190:193], v[40:43]
	v_mfma_f32_16x16x32_f16 v[28:31], v[150:153], v[198:201], v[28:31]
	v_mfma_f32_16x16x32_f16 v[24:27], v[158:161], v[198:201], v[24:27]
	v_mfma_f32_16x16x32_f16 v[12:15], v[150:153], v[206:209], v[12:15]
	v_mfma_f32_16x16x32_f16 v[8:11], v[158:161], v[206:209], v[8:11]
	v_mfma_f32_16x16x32_f16 v[52:55], v[162:165], v[178:181], 0
	v_mfma_f32_16x16x32_f16 v[48:51], v[170:173], v[178:181], 0
	v_mfma_f32_16x16x32_f16 v[36:39], v[162:165], v[186:189], 0
	v_mfma_f32_16x16x32_f16 v[32:35], v[170:173], v[186:189], 0
	v_mfma_f32_16x16x32_f16 v[20:23], v[162:165], v[194:197], 0
	v_mfma_f32_16x16x32_f16 v[16:19], v[170:173], v[194:197], 0
	v_mfma_f32_16x16x32_f16 v[4:7], v[162:165], v[202:205], 0
	v_mfma_f32_16x16x32_f16 v[0:3], v[170:173], v[202:205], 0
	v_mfma_f32_16x16x32_f16 v[52:55], v[166:169], v[182:185], v[52:55]
	v_mfma_f32_16x16x32_f16 v[48:51], v[174:177], v[182:185], v[48:51]
	v_mfma_f32_16x16x32_f16 v[36:39], v[166:169], v[190:193], v[36:39]
	v_mfma_f32_16x16x32_f16 v[32:35], v[174:177], v[190:193], v[32:35]
	v_mfma_f32_16x16x32_f16 v[20:23], v[166:169], v[198:201], v[20:23]
	v_mfma_f32_16x16x32_f16 v[16:19], v[174:177], v[198:201], v[16:19]
	v_mfma_f32_16x16x32_f16 v[4:7], v[166:169], v[206:209], v[4:7]
	v_mfma_f32_16x16x32_f16 v[0:3], v[174:177], v[206:209], v[0:3]
	s_barrier
	s_add_i32 s43, 0, 0x18000
	s_add_i32 s44, 0, 0x1c000
	v_add_u32_e32 v158, s43, v144
	v_add_u32_e32 v174, s44, v144
	ds_read_b128 v[146:149], v158
	ds_read_b128 v[150:153], v158 offset:1024
	ds_read_b128 v[154:157], v158 offset:2048
	ds_read_b128 v[158:161], v158 offset:3072
	ds_read_b128 v[162:165], v174
	ds_read_b128 v[166:169], v174 offset:1024
	ds_read_b128 v[170:173], v174 offset:2048
	ds_read_b128 v[174:177], v174 offset:3072
	s_add_u32 s18, s18, 0x40000
	s_addc_u32 s19, s19, 0
	s_mov_b32 m0, s34
	v_lshl_add_u64 v[218:219], s[18:19], 0, v[130:131]
	ds_read_b128 v[178:181], v145 offset:32768
	ds_read_b128 v[182:185], v145 offset:33792
	ds_read_b128 v[186:189], v145 offset:34816
	ds_read_b128 v[190:193], v145 offset:35840
	ds_read_b128 v[194:197], v145 offset:36864
	ds_read_b128 v[198:201], v145 offset:37888
	ds_read_b128 v[202:205], v145 offset:38912
	ds_read_b128 v[206:209], v145 offset:39936
	global_load_lds_dwordx4 v[218:219], off sc1
	v_lshl_add_u64 v[218:219], s[18:19], 0, v[132:133]
	s_mov_b32 m0, s35
	s_nop 0
	global_load_lds_dwordx4 v[218:219], off sc1
	s_waitcnt vmcnt(8)
	s_waitcnt lgkmcnt(0)
	s_barrier
	s_waitcnt lgkmcnt(0)
	v_mfma_f32_16x16x32_f16 v[124:127], v[146:149], v[178:181], v[124:127]
	v_mfma_f32_16x16x32_f16 v[120:123], v[154:157], v[178:181], v[120:123]
	v_mfma_f32_16x16x32_f16 v[108:111], v[146:149], v[186:189], v[108:111]
	v_mfma_f32_16x16x32_f16 v[104:107], v[154:157], v[186:189], v[104:107]
	v_mfma_f32_16x16x32_f16 v[92:95], v[146:149], v[194:197], v[92:95]
	v_mfma_f32_16x16x32_f16 v[88:91], v[154:157], v[194:197], v[88:91]
	v_mfma_f32_16x16x32_f16 v[76:79], v[146:149], v[202:205], v[76:79]
	v_mfma_f32_16x16x32_f16 v[72:75], v[154:157], v[202:205], v[72:75]
	v_mfma_f32_16x16x32_f16 v[124:127], v[150:153], v[182:185], v[124:127]
	v_mfma_f32_16x16x32_f16 v[120:123], v[158:161], v[182:185], v[120:123]
	v_mfma_f32_16x16x32_f16 v[108:111], v[150:153], v[190:193], v[108:111]
	v_mfma_f32_16x16x32_f16 v[104:107], v[158:161], v[190:193], v[104:107]
	v_mfma_f32_16x16x32_f16 v[92:95], v[150:153], v[198:201], v[92:95]
	v_mfma_f32_16x16x32_f16 v[88:91], v[158:161], v[198:201], v[88:91]
	v_mfma_f32_16x16x32_f16 v[76:79], v[150:153], v[206:209], v[76:79]
	v_mfma_f32_16x16x32_f16 v[72:75], v[158:161], v[206:209], v[72:75]
	v_mfma_f32_16x16x32_f16 v[116:119], v[162:165], v[178:181], v[116:119]
	v_mfma_f32_16x16x32_f16 v[112:115], v[170:173], v[178:181], v[112:115]
	v_mfma_f32_16x16x32_f16 v[100:103], v[162:165], v[186:189], v[100:103]
	v_mfma_f32_16x16x32_f16 v[96:99], v[170:173], v[186:189], v[96:99]
	v_mfma_f32_16x16x32_f16 v[84:87], v[162:165], v[194:197], v[84:87]
	v_mfma_f32_16x16x32_f16 v[80:83], v[170:173], v[194:197], v[80:83]
	v_mfma_f32_16x16x32_f16 v[68:71], v[162:165], v[202:205], v[68:71]
	v_mfma_f32_16x16x32_f16 v[64:67], v[170:173], v[202:205], v[64:67]
	v_mfma_f32_16x16x32_f16 v[116:119], v[166:169], v[182:185], v[116:119]
	v_mfma_f32_16x16x32_f16 v[112:115], v[174:177], v[182:185], v[112:115]
	v_mfma_f32_16x16x32_f16 v[100:103], v[166:169], v[190:193], v[100:103]
	v_mfma_f32_16x16x32_f16 v[96:99], v[174:177], v[190:193], v[96:99]
	v_mfma_f32_16x16x32_f16 v[84:87], v[166:169], v[198:201], v[84:87]
	v_mfma_f32_16x16x32_f16 v[80:83], v[174:177], v[198:201], v[80:83]
	v_mfma_f32_16x16x32_f16 v[68:71], v[166:169], v[206:209], v[68:71]
	v_mfma_f32_16x16x32_f16 v[64:67], v[174:177], v[206:209], v[64:67]
	s_barrier
	s_add_i32 s18, s43, s66
	v_lshl_add_u64 v[210:211], v[210:211], 0, s[6:7]
	s_mov_b32 m0, s18
	ds_read_b128 v[178:181], v145 offset:49152
	ds_read_b128 v[182:185], v145 offset:50176
	ds_read_b128 v[186:189], v145 offset:51200
	ds_read_b128 v[190:193], v145 offset:52224
	ds_read_b128 v[194:197], v145 offset:53248
	ds_read_b128 v[198:201], v145 offset:54272
	ds_read_b128 v[202:205], v145 offset:55296
	ds_read_b128 v[206:209], v145 offset:56320
	global_load_lds_dwordx4 v[210:211], off
	s_add_i32 m0, s18, 0x2000
	s_add_u32 s16, s16, 0x40080
	v_lshl_add_u64 v[210:211], v[212:213], 0, s[6:7]
	s_addc_u32 s17, s17, 0
	s_add_i32 s18, s44, s66
	global_load_lds_dwordx4 v[210:211], off
	v_lshl_add_u64 v[210:211], s[16:17], 0, v[128:129]
	s_mov_b32 m0, s18
	s_nop 0
	global_load_lds_dwordx4 v[210:211], off
	v_lshl_add_u64 v[210:211], s[16:17], 0, v[134:135]
	s_add_i32 m0, s18, 0x2000
	s_nop 0
	global_load_lds_dwordx4 v[210:211], off
	v_lshl_add_u64 v[210:211], v[214:215], 0, s[6:7]
	s_mov_b32 m0, s36
	s_nop 0
	global_load_lds_dwordx4 v[210:211], off sc1
	v_lshl_add_u64 v[210:211], v[216:217], 0, s[6:7]
	s_mov_b32 m0, s37
	s_nop 0
	global_load_lds_dwordx4 v[210:211], off sc1
	s_waitcnt vmcnt(8)
	s_waitcnt lgkmcnt(0)
	s_barrier
	s_waitcnt lgkmcnt(0)
	v_mfma_f32_16x16x32_f16 v[60:63], v[146:149], v[178:181], v[60:63]
	v_mfma_f32_16x16x32_f16 v[56:59], v[154:157], v[178:181], v[56:59]
	v_mfma_f32_16x16x32_f16 v[44:47], v[146:149], v[186:189], v[44:47]
	v_mfma_f32_16x16x32_f16 v[40:43], v[154:157], v[186:189], v[40:43]
	v_mfma_f32_16x16x32_f16 v[28:31], v[146:149], v[194:197], v[28:31]
	v_mfma_f32_16x16x32_f16 v[24:27], v[154:157], v[194:197], v[24:27]
	v_mfma_f32_16x16x32_f16 v[12:15], v[146:149], v[202:205], v[12:15]
	v_mfma_f32_16x16x32_f16 v[8:11], v[154:157], v[202:205], v[8:11]
	v_mfma_f32_16x16x32_f16 v[60:63], v[150:153], v[182:185], v[60:63]
	v_mfma_f32_16x16x32_f16 v[56:59], v[158:161], v[182:185], v[56:59]
	v_mfma_f32_16x16x32_f16 v[44:47], v[150:153], v[190:193], v[44:47]
	v_mfma_f32_16x16x32_f16 v[40:43], v[158:161], v[190:193], v[40:43]
	v_mfma_f32_16x16x32_f16 v[28:31], v[150:153], v[198:201], v[28:31]
	v_mfma_f32_16x16x32_f16 v[24:27], v[158:161], v[198:201], v[24:27]
	v_mfma_f32_16x16x32_f16 v[12:15], v[150:153], v[206:209], v[12:15]
	v_mfma_f32_16x16x32_f16 v[8:11], v[158:161], v[206:209], v[8:11]
	v_mfma_f32_16x16x32_f16 v[52:55], v[162:165], v[178:181], v[52:55]
	v_mfma_f32_16x16x32_f16 v[48:51], v[170:173], v[178:181], v[48:51]
	v_mfma_f32_16x16x32_f16 v[36:39], v[162:165], v[186:189], v[36:39]
	v_mfma_f32_16x16x32_f16 v[32:35], v[170:173], v[186:189], v[32:35]
	v_mfma_f32_16x16x32_f16 v[20:23], v[162:165], v[194:197], v[20:23]
	v_mfma_f32_16x16x32_f16 v[16:19], v[170:173], v[194:197], v[16:19]
	v_mfma_f32_16x16x32_f16 v[4:7], v[162:165], v[202:205], v[4:7]
	v_mfma_f32_16x16x32_f16 v[0:3], v[170:173], v[202:205], v[0:3]
	v_mfma_f32_16x16x32_f16 v[52:55], v[166:169], v[182:185], v[52:55]
	v_mfma_f32_16x16x32_f16 v[48:51], v[174:177], v[182:185], v[48:51]
	v_mfma_f32_16x16x32_f16 v[36:39], v[166:169], v[190:193], v[36:39]
	v_mfma_f32_16x16x32_f16 v[32:35], v[174:177], v[190:193], v[32:35]
	v_mfma_f32_16x16x32_f16 v[20:23], v[166:169], v[198:201], v[20:23]
	v_mfma_f32_16x16x32_f16 v[16:19], v[174:177], v[198:201], v[16:19]
	v_mfma_f32_16x16x32_f16 v[4:7], v[166:169], v[206:209], v[4:7]
	v_mfma_f32_16x16x32_f16 v[0:3], v[174:177], v[206:209], v[0:3]
	s_barrier
	s_add_i32 s42, s42, 2
	s_add_u32 s14, s14, 0x100
	s_addc_u32 s15, s15, 0
	s_cmp_gt_u32 s42, 13
.LBB0_1232:
	s_add_u32 s16, s38, s14
	s_addc_u32 s17, s39, s15
	s_add_u32 s16, s16, 0x13d00100
	s_addc_u32 s17, s17, 0
	s_add_u32 s43, s40, s14
	s_addc_u32 s44, s41, s15
	s_cmpk_eq_i32 s14, 0x700
	s_cselect_b32 s19, s11, s17
	s_cselect_b32 s18, s10, s16
	s_cselect_b32 s17, s13, s44
	s_cselect_b32 s16, s12, s43
	s_add_i32 s43, 0, 0x14000
	v_add_u32_e32 v158, s67, v144
	v_add_u32_e32 v174, s43, v144
	ds_read_b128 v[146:149], v158
	ds_read_b128 v[150:153], v158 offset:1024
	ds_read_b128 v[154:157], v158 offset:2048
	ds_read_b128 v[158:161], v158 offset:3072
	ds_read_b128 v[162:165], v174
	ds_read_b128 v[166:169], v174 offset:1024
	ds_read_b128 v[170:173], v174 offset:2048
	ds_read_b128 v[174:177], v174 offset:3072
	v_lshl_add_u64 v[210:211], v[136:137], 0, s[14:15]
	s_add_i32 m0, s30, 0xc000
	ds_read_b128 v[178:181], v145
	ds_read_b128 v[182:185], v145 offset:1024
	ds_read_b128 v[186:189], v145 offset:2048
	ds_read_b128 v[190:193], v145 offset:3072
	ds_read_b128 v[194:197], v145 offset:4096
	ds_read_b128 v[198:201], v145 offset:5120
	ds_read_b128 v[202:205], v145 offset:6144
	ds_read_b128 v[206:209], v145 offset:7168
	global_load_lds_dwordx4 v[210:211], off sc1
	v_lshl_add_u64 v[210:211], v[138:139], 0, s[14:15]
	s_add_i32 m0, s30, 0xe000
	s_nop 0
	global_load_lds_dwordx4 v[210:211], off sc1
	s_waitcnt vmcnt(8)
	s_waitcnt lgkmcnt(0)
	s_barrier
	s_waitcnt lgkmcnt(0)
	v_mfma_f32_16x16x32_f16 v[124:127], v[146:149], v[178:181], v[124:127]
	v_mfma_f32_16x16x32_f16 v[120:123], v[154:157], v[178:181], v[120:123]
	v_mfma_f32_16x16x32_f16 v[108:111], v[146:149], v[186:189], v[108:111]
	v_mfma_f32_16x16x32_f16 v[104:107], v[154:157], v[186:189], v[104:107]
	v_mfma_f32_16x16x32_f16 v[92:95], v[146:149], v[194:197], v[92:95]
	v_mfma_f32_16x16x32_f16 v[88:91], v[154:157], v[194:197], v[88:91]
	v_mfma_f32_16x16x32_f16 v[76:79], v[146:149], v[202:205], v[76:79]
	v_mfma_f32_16x16x32_f16 v[72:75], v[154:157], v[202:205], v[72:75]
	v_mfma_f32_16x16x32_f16 v[124:127], v[150:153], v[182:185], v[124:127]
	v_mfma_f32_16x16x32_f16 v[120:123], v[158:161], v[182:185], v[120:123]
	v_mfma_f32_16x16x32_f16 v[108:111], v[150:153], v[190:193], v[108:111]
	v_mfma_f32_16x16x32_f16 v[104:107], v[158:161], v[190:193], v[104:107]
	v_mfma_f32_16x16x32_f16 v[92:95], v[150:153], v[198:201], v[92:95]
	v_mfma_f32_16x16x32_f16 v[88:91], v[158:161], v[198:201], v[88:91]
	v_mfma_f32_16x16x32_f16 v[76:79], v[150:153], v[206:209], v[76:79]
	v_mfma_f32_16x16x32_f16 v[72:75], v[158:161], v[206:209], v[72:75]
	v_mfma_f32_16x16x32_f16 v[116:119], v[162:165], v[178:181], v[116:119]
	v_mfma_f32_16x16x32_f16 v[112:115], v[170:173], v[178:181], v[112:115]
	v_mfma_f32_16x16x32_f16 v[100:103], v[162:165], v[186:189], v[100:103]
	v_mfma_f32_16x16x32_f16 v[96:99], v[170:173], v[186:189], v[96:99]
	v_mfma_f32_16x16x32_f16 v[84:87], v[162:165], v[194:197], v[84:87]
	v_mfma_f32_16x16x32_f16 v[80:83], v[170:173], v[194:197], v[80:83]
	v_mfma_f32_16x16x32_f16 v[68:71], v[162:165], v[202:205], v[68:71]
	v_mfma_f32_16x16x32_f16 v[64:67], v[170:173], v[202:205], v[64:67]
	v_mfma_f32_16x16x32_f16 v[116:119], v[166:169], v[182:185], v[116:119]
	v_mfma_f32_16x16x32_f16 v[112:115], v[174:177], v[182:185], v[112:115]
	v_mfma_f32_16x16x32_f16 v[100:103], v[166:169], v[190:193], v[100:103]
	v_mfma_f32_16x16x32_f16 v[96:99], v[174:177], v[190:193], v[96:99]
	v_mfma_f32_16x16x32_f16 v[84:87], v[166:169], v[198:201], v[84:87]
	v_mfma_f32_16x16x32_f16 v[80:83], v[174:177], v[198:201], v[80:83]
	v_mfma_f32_16x16x32_f16 v[68:71], v[166:169], v[206:209], v[68:71]
	v_mfma_f32_16x16x32_f16 v[64:67], v[174:177], v[206:209], v[64:67]
	s_barrier
	s_add_i32 s44, s67, s66
	v_lshl_add_u64 v[210:211], s[16:17], 0, v[128:129]
	s_mov_b32 m0, s44
	ds_read_b128 v[178:181], v145 offset:16384
	ds_read_b128 v[182:185], v145 offset:17408
	ds_read_b128 v[186:189], v145 offset:18432
	ds_read_b128 v[190:193], v145 offset:19456
	ds_read_b128 v[194:197], v145 offset:20480
	ds_read_b128 v[198:201], v145 offset:21504
	ds_read_b128 v[202:205], v145 offset:22528
	ds_read_b128 v[206:209], v145 offset:23552
	global_load_lds_dwordx4 v[210:211], off
	s_add_i32 m0, s44, 0x2000
	s_add_u32 s44, s16, 0x40000
	v_lshl_add_u64 v[212:213], s[16:17], 0, v[134:135]
	s_addc_u32 s45, s17, 0
	s_add_i32 s43, s43, s66
	global_load_lds_dwordx4 v[212:213], off
	v_lshl_add_u64 v[214:215], s[44:45], 0, v[128:129]
	s_mov_b32 m0, s43
	v_lshl_add_u64 v[216:217], s[18:19], 0, v[132:133]
	global_load_lds_dwordx4 v[214:215], off
	v_lshl_add_u64 v[214:215], s[44:45], 0, v[134:135]
	s_add_i32 m0, s43, 0x2000
	s_nop 0
	global_load_lds_dwordx4 v[214:215], off
	v_lshl_add_u64 v[214:215], s[18:19], 0, v[130:131]
	s_mov_b32 m0, s30
	s_nop 0
	global_load_lds_dwordx4 v[214:215], off sc1
	s_mov_b32 m0, s31
	s_nop 0
	global_load_lds_dwordx4 v[216:217], off sc1
	s_waitcnt vmcnt(8)
	s_waitcnt lgkmcnt(0)
	s_barrier
	s_waitcnt lgkmcnt(0)
	v_mfma_f32_16x16x32_f16 v[60:63], v[146:149], v[178:181], v[60:63]
	v_mfma_f32_16x16x32_f16 v[56:59], v[154:157], v[178:181], v[56:59]
	v_mfma_f32_16x16x32_f16 v[44:47], v[146:149], v[186:189], v[44:47]
	v_mfma_f32_16x16x32_f16 v[40:43], v[154:157], v[186:189], v[40:43]
	v_mfma_f32_16x16x32_f16 v[28:31], v[146:149], v[194:197], v[28:31]
	v_mfma_f32_16x16x32_f16 v[24:27], v[154:157], v[194:197], v[24:27]
	v_mfma_f32_16x16x32_f16 v[12:15], v[146:149], v[202:205], v[12:15]
	v_mfma_f32_16x16x32_f16 v[8:11], v[154:157], v[202:205], v[8:11]
	v_mfma_f32_16x16x32_f16 v[60:63], v[150:153], v[182:185], v[60:63]
	v_mfma_f32_16x16x32_f16 v[56:59], v[158:161], v[182:185], v[56:59]
	v_mfma_f32_16x16x32_f16 v[44:47], v[150:153], v[190:193], v[44:47]
	v_mfma_f32_16x16x32_f16 v[40:43], v[158:161], v[190:193], v[40:43]
	v_mfma_f32_16x16x32_f16 v[28:31], v[150:153], v[198:201], v[28:31]
	v_mfma_f32_16x16x32_f16 v[24:27], v[158:161], v[198:201], v[24:27]
	v_mfma_f32_16x16x32_f16 v[12:15], v[150:153], v[206:209], v[12:15]
	v_mfma_f32_16x16x32_f16 v[8:11], v[158:161], v[206:209], v[8:11]
	v_mfma_f32_16x16x32_f16 v[52:55], v[162:165], v[178:181], v[52:55]
	v_mfma_f32_16x16x32_f16 v[48:51], v[170:173], v[178:181], v[48:51]
	v_mfma_f32_16x16x32_f16 v[36:39], v[162:165], v[186:189], v[36:39]
	v_mfma_f32_16x16x32_f16 v[32:35], v[170:173], v[186:189], v[32:35]
	v_mfma_f32_16x16x32_f16 v[20:23], v[162:165], v[194:197], v[20:23]
	v_mfma_f32_16x16x32_f16 v[16:19], v[170:173], v[194:197], v[16:19]
	v_mfma_f32_16x16x32_f16 v[4:7], v[162:165], v[202:205], v[4:7]
	v_mfma_f32_16x16x32_f16 v[0:3], v[170:173], v[202:205], v[0:3]
	v_mfma_f32_16x16x32_f16 v[52:55], v[166:169], v[182:185], v[52:55]
	v_mfma_f32_16x16x32_f16 v[48:51], v[174:177], v[182:185], v[48:51]
	v_mfma_f32_16x16x32_f16 v[36:39], v[166:169], v[190:193], v[36:39]
	v_mfma_f32_16x16x32_f16 v[32:35], v[174:177], v[190:193], v[32:35]
	v_mfma_f32_16x16x32_f16 v[20:23], v[166:169], v[198:201], v[20:23]
	v_mfma_f32_16x16x32_f16 v[16:19], v[174:177], v[198:201], v[16:19]
	v_mfma_f32_16x16x32_f16 v[4:7], v[166:169], v[206:209], v[4:7]
	v_mfma_f32_16x16x32_f16 v[0:3], v[174:177], v[206:209], v[0:3]
	s_barrier
	s_add_i32 s43, 0, 0x18000
	s_add_i32 s44, 0, 0x1c000
	v_add_u32_e32 v158, s43, v144
	v_add_u32_e32 v174, s44, v144
	ds_read_b128 v[146:149], v158
	ds_read_b128 v[150:153], v158 offset:1024
	ds_read_b128 v[154:157], v158 offset:2048
	ds_read_b128 v[158:161], v158 offset:3072
	ds_read_b128 v[162:165], v174
	ds_read_b128 v[166:169], v174 offset:1024
	ds_read_b128 v[170:173], v174 offset:2048
	ds_read_b128 v[174:177], v174 offset:3072
	s_add_u32 s18, s18, 0x40000
	s_addc_u32 s19, s19, 0
	s_mov_b32 m0, s34
	v_lshl_add_u64 v[218:219], s[18:19], 0, v[130:131]
	ds_read_b128 v[178:181], v145 offset:32768
	ds_read_b128 v[182:185], v145 offset:33792
	ds_read_b128 v[186:189], v145 offset:34816
	ds_read_b128 v[190:193], v145 offset:35840
	ds_read_b128 v[194:197], v145 offset:36864
	ds_read_b128 v[198:201], v145 offset:37888
	ds_read_b128 v[202:205], v145 offset:38912
	ds_read_b128 v[206:209], v145 offset:39936
	global_load_lds_dwordx4 v[218:219], off sc1
	v_lshl_add_u64 v[218:219], s[18:19], 0, v[132:133]
	s_mov_b32 m0, s35
	s_nop 0
	global_load_lds_dwordx4 v[218:219], off sc1
	s_waitcnt vmcnt(8)
	s_waitcnt lgkmcnt(0)
	s_barrier
	s_waitcnt lgkmcnt(0)
	v_mfma_f32_16x16x32_f16 v[124:127], v[146:149], v[178:181], v[124:127]
	v_mfma_f32_16x16x32_f16 v[120:123], v[154:157], v[178:181], v[120:123]
	v_mfma_f32_16x16x32_f16 v[108:111], v[146:149], v[186:189], v[108:111]
	v_mfma_f32_16x16x32_f16 v[104:107], v[154:157], v[186:189], v[104:107]
	v_mfma_f32_16x16x32_f16 v[92:95], v[146:149], v[194:197], v[92:95]
	v_mfma_f32_16x16x32_f16 v[88:91], v[154:157], v[194:197], v[88:91]
	v_mfma_f32_16x16x32_f16 v[76:79], v[146:149], v[202:205], v[76:79]
	v_mfma_f32_16x16x32_f16 v[72:75], v[154:157], v[202:205], v[72:75]
	v_mfma_f32_16x16x32_f16 v[124:127], v[150:153], v[182:185], v[124:127]
	v_mfma_f32_16x16x32_f16 v[120:123], v[158:161], v[182:185], v[120:123]
	v_mfma_f32_16x16x32_f16 v[108:111], v[150:153], v[190:193], v[108:111]
	v_mfma_f32_16x16x32_f16 v[104:107], v[158:161], v[190:193], v[104:107]
	v_mfma_f32_16x16x32_f16 v[92:95], v[150:153], v[198:201], v[92:95]
	v_mfma_f32_16x16x32_f16 v[88:91], v[158:161], v[198:201], v[88:91]
	v_mfma_f32_16x16x32_f16 v[76:79], v[150:153], v[206:209], v[76:79]
	v_mfma_f32_16x16x32_f16 v[72:75], v[158:161], v[206:209], v[72:75]
	v_mfma_f32_16x16x32_f16 v[116:119], v[162:165], v[178:181], v[116:119]
	v_mfma_f32_16x16x32_f16 v[112:115], v[170:173], v[178:181], v[112:115]
	v_mfma_f32_16x16x32_f16 v[100:103], v[162:165], v[186:189], v[100:103]
	v_mfma_f32_16x16x32_f16 v[96:99], v[170:173], v[186:189], v[96:99]
	v_mfma_f32_16x16x32_f16 v[84:87], v[162:165], v[194:197], v[84:87]
	v_mfma_f32_16x16x32_f16 v[80:83], v[170:173], v[194:197], v[80:83]
	v_mfma_f32_16x16x32_f16 v[68:71], v[162:165], v[202:205], v[68:71]
	v_mfma_f32_16x16x32_f16 v[64:67], v[170:173], v[202:205], v[64:67]
	v_mfma_f32_16x16x32_f16 v[116:119], v[166:169], v[182:185], v[116:119]
	v_mfma_f32_16x16x32_f16 v[112:115], v[174:177], v[182:185], v[112:115]
	v_mfma_f32_16x16x32_f16 v[100:103], v[166:169], v[190:193], v[100:103]
	v_mfma_f32_16x16x32_f16 v[96:99], v[174:177], v[190:193], v[96:99]
	v_mfma_f32_16x16x32_f16 v[84:87], v[166:169], v[198:201], v[84:87]
	v_mfma_f32_16x16x32_f16 v[80:83], v[174:177], v[198:201], v[80:83]
	v_mfma_f32_16x16x32_f16 v[68:71], v[166:169], v[206:209], v[68:71]
	v_mfma_f32_16x16x32_f16 v[64:67], v[174:177], v[206:209], v[64:67]
	s_barrier
	s_add_i32 s18, s43, s66
	v_lshl_add_u64 v[210:211], v[210:211], 0, s[6:7]
	s_mov_b32 m0, s18
	ds_read_b128 v[178:181], v145 offset:49152
	ds_read_b128 v[182:185], v145 offset:50176
	ds_read_b128 v[186:189], v145 offset:51200
	ds_read_b128 v[190:193], v145 offset:52224
	ds_read_b128 v[194:197], v145 offset:53248
	ds_read_b128 v[198:201], v145 offset:54272
	ds_read_b128 v[202:205], v145 offset:55296
	ds_read_b128 v[206:209], v145 offset:56320
	global_load_lds_dwordx4 v[210:211], off
	s_add_i32 m0, s18, 0x2000
	s_add_u32 s16, s16, 0x40080
	v_lshl_add_u64 v[210:211], v[212:213], 0, s[6:7]
	s_addc_u32 s17, s17, 0
	s_add_i32 s18, s44, s66
	global_load_lds_dwordx4 v[210:211], off
	v_lshl_add_u64 v[210:211], s[16:17], 0, v[128:129]
	s_mov_b32 m0, s18
	s_nop 0
	global_load_lds_dwordx4 v[210:211], off
	v_lshl_add_u64 v[210:211], s[16:17], 0, v[134:135]
	s_add_i32 m0, s18, 0x2000
	s_nop 0
	global_load_lds_dwordx4 v[210:211], off
	v_lshl_add_u64 v[210:211], v[214:215], 0, s[6:7]
	s_mov_b32 m0, s36
	s_nop 0
	global_load_lds_dwordx4 v[210:211], off sc1
	v_lshl_add_u64 v[210:211], v[216:217], 0, s[6:7]
	s_mov_b32 m0, s37
	s_nop 0
	global_load_lds_dwordx4 v[210:211], off sc1
	s_waitcnt vmcnt(8)
	s_waitcnt lgkmcnt(0)
	s_barrier
	s_waitcnt lgkmcnt(0)
	v_mfma_f32_16x16x32_f16 v[60:63], v[146:149], v[178:181], v[60:63]
	v_mfma_f32_16x16x32_f16 v[56:59], v[154:157], v[178:181], v[56:59]
	v_mfma_f32_16x16x32_f16 v[44:47], v[146:149], v[186:189], v[44:47]
	v_mfma_f32_16x16x32_f16 v[40:43], v[154:157], v[186:189], v[40:43]
	v_mfma_f32_16x16x32_f16 v[28:31], v[146:149], v[194:197], v[28:31]
	v_mfma_f32_16x16x32_f16 v[24:27], v[154:157], v[194:197], v[24:27]
	v_mfma_f32_16x16x32_f16 v[12:15], v[146:149], v[202:205], v[12:15]
	v_mfma_f32_16x16x32_f16 v[8:11], v[154:157], v[202:205], v[8:11]
	v_mfma_f32_16x16x32_f16 v[60:63], v[150:153], v[182:185], v[60:63]
	v_mfma_f32_16x16x32_f16 v[56:59], v[158:161], v[182:185], v[56:59]
	v_mfma_f32_16x16x32_f16 v[44:47], v[150:153], v[190:193], v[44:47]
	v_mfma_f32_16x16x32_f16 v[40:43], v[158:161], v[190:193], v[40:43]
	v_mfma_f32_16x16x32_f16 v[28:31], v[150:153], v[198:201], v[28:31]
	v_mfma_f32_16x16x32_f16 v[24:27], v[158:161], v[198:201], v[24:27]
	v_mfma_f32_16x16x32_f16 v[12:15], v[150:153], v[206:209], v[12:15]
	v_mfma_f32_16x16x32_f16 v[8:11], v[158:161], v[206:209], v[8:11]
	v_mfma_f32_16x16x32_f16 v[52:55], v[162:165], v[178:181], v[52:55]
	v_mfma_f32_16x16x32_f16 v[48:51], v[170:173], v[178:181], v[48:51]
	v_mfma_f32_16x16x32_f16 v[36:39], v[162:165], v[186:189], v[36:39]
	v_mfma_f32_16x16x32_f16 v[32:35], v[170:173], v[186:189], v[32:35]
	v_mfma_f32_16x16x32_f16 v[20:23], v[162:165], v[194:197], v[20:23]
	v_mfma_f32_16x16x32_f16 v[16:19], v[170:173], v[194:197], v[16:19]
	v_mfma_f32_16x16x32_f16 v[4:7], v[162:165], v[202:205], v[4:7]
	v_mfma_f32_16x16x32_f16 v[0:3], v[170:173], v[202:205], v[0:3]
	v_mfma_f32_16x16x32_f16 v[52:55], v[166:169], v[182:185], v[52:55]
	v_mfma_f32_16x16x32_f16 v[48:51], v[174:177], v[182:185], v[48:51]
	v_mfma_f32_16x16x32_f16 v[36:39], v[166:169], v[190:193], v[36:39]
	v_mfma_f32_16x16x32_f16 v[32:35], v[174:177], v[190:193], v[32:35]
	v_mfma_f32_16x16x32_f16 v[20:23], v[166:169], v[198:201], v[20:23]
	v_mfma_f32_16x16x32_f16 v[16:19], v[174:177], v[198:201], v[16:19]
	v_mfma_f32_16x16x32_f16 v[4:7], v[166:169], v[206:209], v[4:7]
	v_mfma_f32_16x16x32_f16 v[0:3], v[174:177], v[206:209], v[0:3]
	s_barrier
	s_add_i32 s42, s42, 2
	s_add_u32 s14, s14, 0x100
	s_addc_u32 s15, s15, 0
	s_cmp_gt_u32 s42, 13
	s_cbranch_scc0 .LBB0_1232
	s_and_b64 vcc, exec, s[26:27]
	s_cbranch_vccz .LBB0_1235
	s_barrier

.Lp4_enter:
	ds_read_b32 v0, v141
	s_waitcnt lgkmcnt(0)
	v_readfirstlane_b32 s0, v0
	s_cmp_eq_u32 s0, -1
	s_cbranch_scc1 .LBB0_1383
	v_mbcnt_lo_u32_b32 v1, -1, 0
	v_mbcnt_hi_u32_b32 v1, -1, v1
	s_lshr_b32 s18, s0, 2
	v_lshl_or_b32 v4, v1, 4, s53
	v_ashrrev_i32_e32 v0, 31, v4
	v_lshrrev_b32_e32 v0, 22, v0
	v_add_u32_e32 v0, v4, v0
	v_ashrrev_i32_e32 v0, 10, v0
	v_mul_i32_i24_e32 v2, 0x400, v0
	v_sub_u32_e32 v2, v4, v2
	v_lshrrev_b32_e32 v3, 4, v2
	v_bitop3_b32 v3, v3, v2, 32 bitop3:0x6c
	v_lshlrev_b32_e32 v2, 3, v0
	v_and_b32_e32 v5, -16, v2
	v_ashrrev_i32_e32 v2, 31, v3
	v_lshrrev_b32_e32 v2, 26, v2
	v_add_u32_e32 v6, v3, v2
	v_ashrrev_i32_e32 v2, 6, v6
	v_and_b32_e32 v6, 0xc0, v6
	v_sub_u32_e32 v3, v3, v6
	v_lshlrev_b32_e32 v7, 5, v0
	v_ashrrev_i16_sdwa v3, v140, sext(v3) dst_sel:DWORD dst_unused:UNUSED_PAD src0_sel:DWORD src1_sel:BYTE_0
	v_and_b32_e32 v7, 32, v7
	v_bfe_i32 v3, v3, 0, 16
	v_add_u32_e32 v5, v2, v5
	v_and_b32_e32 v9, 3, v2
	v_add_lshl_u32 v7, v7, v3, 1
	v_lshlrev_b32_e32 v6, 1, v5
	v_lshrrev_b32_e32 v8, 2, v5
	v_and_or_b32 v9, v5, s65, v9
	v_lshl_add_u32 v130, v5, 11, v7
	v_add_u32_e32 v5, 0x2000, v4
	v_ashrrev_i32_e32 v4, 31, v5
	v_lshrrev_b32_e32 v4, 22, v4
	v_and_b32_e32 v6, 24, v6
	v_and_b32_e32 v8, 4, v8
	v_add_u32_e32 v4, v5, v4
	v_or3_b32 v6, v9, v8, v6
	v_ashrrev_i32_e32 v4, 10, v4
	v_lshl_add_u32 v128, v6, 11, v7
	v_mul_i32_i24_e32 v6, 0x400, v4
	v_sub_u32_e32 v5, v5, v6
	v_lshrrev_b32_e32 v6, 4, v5
	v_bitop3_b32 v6, v6, v5, 32 bitop3:0x6c
	v_lshlrev_b32_e32 v5, 3, v4
	v_and_b32_e32 v7, -16, v5
	v_ashrrev_i32_e32 v5, 31, v6
	v_lshrrev_b32_e32 v5, 26, v5
	v_add_u32_e32 v8, v6, v5
	v_ashrrev_i32_e32 v5, 6, v8
	v_and_b32_e32 v8, 0xffc0, v8
	v_sub_u32_e32 v6, v6, v8
	s_and_b32 s34, s0, 3
	v_lshrrev_b16_e32 v8, 7, v6
	v_and_b32_e32 v8, 1, v8
	s_lshl_b64 s[26:27], s[18:19], 19
	s_lshl_b32 s28, s34, 19
	v_add_u32_e32 v7, v5, v7
	v_add_u16_e32 v6, v6, v8
	s_add_u32 s0, s50, s28
	v_lshlrev_b32_e32 v9, 5, v4
	v_ashrrev_i16_sdwa v6, v140, sext(v6) dst_sel:DWORD dst_unused:UNUSED_PAD src0_sel:DWORD src1_sel:BYTE_0
	v_lshlrev_b32_e32 v8, 1, v7
	v_lshrrev_b32_e32 v10, 2, v7
	v_and_b32_e32 v11, 3, v5
	s_addc_u32 s1, s51, 0
	s_add_i32 s35, s53, 0
	v_and_b32_e32 v9, 32, v9
	v_bfe_i32 v6, v6, 0, 16
	v_and_b32_e32 v8, 24, v8
	v_and_b32_e32 v10, 4, v10
	v_and_or_b32 v11, v7, s65, v11
	s_add_i32 m0, s35, 0x10000
	v_or3_b32 v8, v11, v10, v8
	v_add_lshl_u32 v9, v9, v6, 1
	global_load_lds_dwordx4 v128, s[0:1]
	s_add_i32 m0, s35, 0x12000
	v_lshl_add_u32 v134, v8, 11, v9
	s_add_u32 s24, s0, 0x40000
	global_load_lds_dwordx4 v134, s[0:1]
	s_addc_u32 s25, s1, 0
	s_add_i32 m0, s35, 0x14000
	v_lshl_add_u32 v132, v7, 11, v9
	global_load_lds_dwordx4 v128, s[24:25]
	s_add_i32 m0, s35, 0x16000
	v_lshl_add_u64 v[8:9], s[0:1], 0, v[128:129]
	global_load_lds_dwordx4 v134, s[24:25]
	s_add_u32 s24, s3, s26
	s_addc_u32 s25, s33, s27
	s_add_i32 s36, s35, 0x2000
	s_mov_b32 m0, s35
	s_add_u32 s30, s24, 0x40000
	global_load_lds_dwordx4 v130, s[24:25] sc1
	s_mov_b32 m0, s36
	s_addc_u32 s31, s25, 0
	s_add_i32 s37, s35, 0x4000
	global_load_lds_dwordx4 v132, s[24:25] sc1
	s_mov_b32 m0, s37
	s_add_i32 s38, s35, 0x6000
	v_mov_b32_e32 v135, v129
	global_load_lds_dwordx4 v130, s[30:31] sc1
	s_mov_b32 m0, s38
	v_lshl_add_u64 v[10:11], s[0:1], 0, v[134:135]
	v_mov_b32_e32 v131, v129
	global_load_lds_dwordx4 v132, s[30:31] sc1
	v_lshl_add_u64 v[8:9], v[8:9], 0, s[20:21]
	s_add_i32 m0, s35, 0x18000
	v_lshl_add_u64 v[12:13], s[24:25], 0, v[130:131]
	v_mov_b32_e32 v133, v129
	global_load_lds_dwordx4 v[8:9], off
	v_lshl_add_u64 v[8:9], v[10:11], 0, s[20:21]
	s_add_i32 m0, s35, 0x1a000
	s_add_i32 s39, s35, 0x8000
	v_lshl_add_u64 v[14:15], s[24:25], 0, v[132:133]
	global_load_lds_dwordx4 v[8:9], off
	v_lshl_add_u64 v[8:9], v[12:13], 0, s[20:21]
	s_mov_b32 m0, s39
	s_add_i32 s40, s35, 0xa000
	global_load_lds_dwordx4 v[8:9], off sc1
	v_lshl_add_u64 v[8:9], v[14:15], 0, s[20:21]
	s_mov_b32 m0, s40
	s_add_u32 s30, s0, 0x40080
	global_load_lds_dwordx4 v[8:9], off sc1
	s_addc_u32 s31, s1, 0
	s_add_i32 m0, s35, 0x1c000
	s_andn2_b64 vcc, exec, s[14:15]
	global_load_lds_dwordx4 v128, s[30:31]
	s_add_i32 m0, s35, 0x1e000
	s_nop 0
	global_load_lds_dwordx4 v134, s[30:31]
	s_cbranch_vccnz .LBB0_1328
	s_barrier
.LBB0_1328:
	v_bfe_u32 v144, v1, 4, 2
	v_and_b32_e32 v7, 15, v1
	v_lshlrev_b32_e32 v145, 4, v144
	v_lshlrev_b32_e32 v1, 2, v1
	v_or_b32_e32 v146, s54, v7
	v_lshl_or_b32 v7, v7, 6, v145
	v_and_b32_e32 v1, 32, v1
	v_bitop3_b32 v147, v7, s56, v1 bitop3:0xde
	v_lshlrev_b32_e32 v1, 14, v0
	s_add_u32 s41, s76, s26
	v_and_b32_e32 v1, 0xffff8000, v1
	s_addc_u32 s42, s77, s27
	v_lshl_add_u32 v1, v2, 11, v1
	v_and_b32_e32 v0, 1, v0
	v_lshl_or_b32 v0, v0, 6, v1
	s_add_u32 s26, s60, s26
	v_lshl_add_u32 v0, v3, 1, v0
	v_mov_b32_e32 v1, v129
	s_addc_u32 s27, s61, s27
	v_lshl_add_u64 v[136:137], s[26:27], 0, v[0:1]
	v_lshlrev_b32_e32 v0, 14, v4
	v_and_b32_e32 v0, 0xffff8000, v0
	v_lshl_add_u32 v0, v5, 11, v0
	v_and_b32_e32 v1, 1, v4
	v_lshlrev_b32_e32 v8, 6, v146
	v_lshlrev_b32_e32 v9, 2, v146
	v_lshl_or_b32 v0, v1, 6, v0
	v_and_or_b32 v8, v8, s66, v145
	v_and_b32_e32 v9, 32, v9
	s_waitcnt vmcnt(8)
	s_barrier
	s_waitcnt vmcnt(6)
	v_lshl_add_u32 v0, v6, 1, v0
	v_mov_b32_e32 v1, v129
	v_bitop3_b32 v7, v8, s55, v9 bitop3:0xde
	v_lshl_add_u64 v[138:139], s[26:27], 0, v[0:1]
	s_add_u32 s43, s62, s28
	s_addc_u32 s44, s63, 0
	s_mov_b32 s45, -2
	s_mov_b64 s[26:27], 0
	v_add_u32_e32 v148, 0, v7
	s_barrier
	s_add_u32 s28, s41, s26
	s_addc_u32 s29, s42, s27
	s_add_u32 s28, s28, 0x7a00100
	s_addc_u32 s29, s29, 0
	s_add_u32 s46, s43, s26
	s_addc_u32 s47, s44, s27
	s_add_i32 s48, 0, 0x10000
	s_cmpk_eq_i32 s26, 0x700
	s_cselect_b32 s31, s25, s29
	s_cselect_b32 s30, s24, s28
	v_add_u32_e32 v149, s48, v147
	s_cselect_b32 s29, s1, s47
	s_cselect_b32 s28, s0, s46
	s_add_i32 s49, 0, 0x14000
	ds_read_b128 v[150:153], v149
	ds_read_b128 v[154:157], v149 offset:1024
	ds_read_b128 v[158:161], v149 offset:2048
	ds_read_b128 v[162:165], v149 offset:3072
	v_add_u32_e32 v149, s49, v147
	ds_read_b128 v[166:169], v149
	ds_read_b128 v[170:173], v149 offset:1024
	ds_read_b128 v[174:177], v149 offset:2048
	ds_read_b128 v[178:181], v149 offset:3072
	v_lshl_add_u64 v[214:215], v[136:137], 0, s[26:27]
	s_add_i32 m0, s35, 0xc000
	ds_read_b128 v[182:185], v148
	ds_read_b128 v[186:189], v148 offset:1024
	ds_read_b128 v[190:193], v148 offset:2048
	ds_read_b128 v[194:197], v148 offset:3072
	ds_read_b128 v[198:201], v148 offset:4096
	ds_read_b128 v[202:205], v148 offset:5120
	ds_read_b128 v[206:209], v148 offset:6144
	ds_read_b128 v[210:213], v148 offset:7168
	global_load_lds_dwordx4 v[214:215], off sc1
	v_lshl_add_u64 v[214:215], v[138:139], 0, s[26:27]
	s_add_i32 m0, s35, 0xe000
	s_nop 0
	global_load_lds_dwordx4 v[214:215], off sc1
	s_waitcnt vmcnt(8)
	s_waitcnt lgkmcnt(0)
	s_barrier
	s_waitcnt lgkmcnt(0)
	v_mfma_f32_16x16x32_f16 v[124:127], v[150:153], v[182:185], 0
	v_mfma_f32_16x16x32_f16 v[120:123], v[158:161], v[182:185], 0
	v_mfma_f32_16x16x32_f16 v[108:111], v[150:153], v[190:193], 0
	v_mfma_f32_16x16x32_f16 v[104:107], v[158:161], v[190:193], 0
	v_mfma_f32_16x16x32_f16 v[92:95], v[150:153], v[198:201], 0
	v_mfma_f32_16x16x32_f16 v[88:91], v[158:161], v[198:201], 0
	v_mfma_f32_16x16x32_f16 v[76:79], v[150:153], v[206:209], 0
	v_mfma_f32_16x16x32_f16 v[72:75], v[158:161], v[206:209], 0
	v_mfma_f32_16x16x32_f16 v[124:127], v[154:157], v[186:189], v[124:127]
	v_mfma_f32_16x16x32_f16 v[120:123], v[162:165], v[186:189], v[120:123]
	v_mfma_f32_16x16x32_f16 v[108:111], v[154:157], v[194:197], v[108:111]
	v_mfma_f32_16x16x32_f16 v[104:107], v[162:165], v[194:197], v[104:107]
	v_mfma_f32_16x16x32_f16 v[92:95], v[154:157], v[202:205], v[92:95]
	v_mfma_f32_16x16x32_f16 v[88:91], v[162:165], v[202:205], v[88:91]
	v_mfma_f32_16x16x32_f16 v[76:79], v[154:157], v[210:213], v[76:79]
	v_mfma_f32_16x16x32_f16 v[72:75], v[162:165], v[210:213], v[72:75]
	v_mfma_f32_16x16x32_f16 v[116:119], v[166:169], v[182:185], 0
	v_mfma_f32_16x16x32_f16 v[112:115], v[174:177], v[182:185], 0
	v_mfma_f32_16x16x32_f16 v[100:103], v[166:169], v[190:193], 0
	v_mfma_f32_16x16x32_f16 v[96:99], v[174:177], v[190:193], 0
	v_mfma_f32_16x16x32_f16 v[84:87], v[166:169], v[198:201], 0
	v_mfma_f32_16x16x32_f16 v[80:83], v[174:177], v[198:201], 0
	v_mfma_f32_16x16x32_f16 v[68:71], v[166:169], v[206:209], 0
	v_mfma_f32_16x16x32_f16 v[64:67], v[174:177], v[206:209], 0
	v_mfma_f32_16x16x32_f16 v[116:119], v[170:173], v[186:189], v[116:119]
	v_mfma_f32_16x16x32_f16 v[112:115], v[178:181], v[186:189], v[112:115]
	v_mfma_f32_16x16x32_f16 v[100:103], v[170:173], v[194:197], v[100:103]
	v_mfma_f32_16x16x32_f16 v[96:99], v[178:181], v[194:197], v[96:99]
	v_mfma_f32_16x16x32_f16 v[84:87], v[170:173], v[202:205], v[84:87]
	v_mfma_f32_16x16x32_f16 v[80:83], v[178:181], v[202:205], v[80:83]
	v_mfma_f32_16x16x32_f16 v[68:71], v[170:173], v[210:213], v[68:71]
	v_mfma_f32_16x16x32_f16 v[64:67], v[178:181], v[210:213], v[64:67]
	s_barrier
	s_add_i32 s46, s48, s53
	v_lshl_add_u64 v[214:215], s[28:29], 0, v[128:129]
	s_mov_b32 m0, s46
	ds_read_b128 v[182:185], v148 offset:16384
	ds_read_b128 v[186:189], v148 offset:17408
	ds_read_b128 v[190:193], v148 offset:18432
	ds_read_b128 v[194:197], v148 offset:19456
	ds_read_b128 v[198:201], v148 offset:20480
	ds_read_b128 v[202:205], v148 offset:21504
	ds_read_b128 v[206:209], v148 offset:22528
	ds_read_b128 v[210:213], v148 offset:23552
	global_load_lds_dwordx4 v[214:215], off
	s_add_i32 m0, s46, 0x2000
	s_add_u32 s46, s28, 0x40000
	v_lshl_add_u64 v[216:217], s[28:29], 0, v[134:135]
	s_addc_u32 s47, s29, 0
	s_add_i32 s48, s49, s53
	global_load_lds_dwordx4 v[216:217], off
	v_lshl_add_u64 v[218:219], s[46:47], 0, v[128:129]
	s_mov_b32 m0, s48
	v_lshl_add_u64 v[220:221], s[30:31], 0, v[132:133]
	global_load_lds_dwordx4 v[218:219], off
	v_lshl_add_u64 v[218:219], s[46:47], 0, v[134:135]
	s_add_i32 m0, s48, 0x2000
	s_nop 0
	global_load_lds_dwordx4 v[218:219], off
	v_lshl_add_u64 v[218:219], s[30:31], 0, v[130:131]
	s_mov_b32 m0, s35
	s_nop 0
	global_load_lds_dwordx4 v[218:219], off sc1
	s_mov_b32 m0, s36
	s_nop 0
	global_load_lds_dwordx4 v[220:221], off sc1
	s_waitcnt vmcnt(8)
	s_waitcnt lgkmcnt(0)
	s_barrier
	s_waitcnt lgkmcnt(0)
	v_mfma_f32_16x16x32_f16 v[60:63], v[150:153], v[182:185], 0
	v_mfma_f32_16x16x32_f16 v[56:59], v[158:161], v[182:185], 0
	v_mfma_f32_16x16x32_f16 v[44:47], v[150:153], v[190:193], 0
	v_mfma_f32_16x16x32_f16 v[40:43], v[158:161], v[190:193], 0
	v_mfma_f32_16x16x32_f16 v[28:31], v[150:153], v[198:201], 0
	v_mfma_f32_16x16x32_f16 v[24:27], v[158:161], v[198:201], 0
	v_mfma_f32_16x16x32_f16 v[12:15], v[150:153], v[206:209], 0
	v_mfma_f32_16x16x32_f16 v[8:11], v[158:161], v[206:209], 0
	v_mfma_f32_16x16x32_f16 v[60:63], v[154:157], v[186:189], v[60:63]
	v_mfma_f32_16x16x32_f16 v[56:59], v[162:165], v[186:189], v[56:59]
	v_mfma_f32_16x16x32_f16 v[44:47], v[154:157], v[194:197], v[44:47]
	v_mfma_f32_16x16x32_f16 v[40:43], v[162:165], v[194:197], v[40:43]
	v_mfma_f32_16x16x32_f16 v[28:31], v[154:157], v[202:205], v[28:31]
	v_mfma_f32_16x16x32_f16 v[24:27], v[162:165], v[202:205], v[24:27]
	v_mfma_f32_16x16x32_f16 v[12:15], v[154:157], v[210:213], v[12:15]
	v_mfma_f32_16x16x32_f16 v[8:11], v[162:165], v[210:213], v[8:11]
	v_mfma_f32_16x16x32_f16 v[52:55], v[166:169], v[182:185], 0
	v_mfma_f32_16x16x32_f16 v[48:51], v[174:177], v[182:185], 0
	v_mfma_f32_16x16x32_f16 v[36:39], v[166:169], v[190:193], 0
	v_mfma_f32_16x16x32_f16 v[32:35], v[174:177], v[190:193], 0
	v_mfma_f32_16x16x32_f16 v[20:23], v[166:169], v[198:201], 0
	v_mfma_f32_16x16x32_f16 v[16:19], v[174:177], v[198:201], 0
	v_mfma_f32_16x16x32_f16 v[4:7], v[166:169], v[206:209], 0
	v_mfma_f32_16x16x32_f16 v[0:3], v[174:177], v[206:209], 0
	v_mfma_f32_16x16x32_f16 v[52:55], v[170:173], v[186:189], v[52:55]
	v_mfma_f32_16x16x32_f16 v[48:51], v[178:181], v[186:189], v[48:51]
	v_mfma_f32_16x16x32_f16 v[36:39], v[170:173], v[194:197], v[36:39]
	v_mfma_f32_16x16x32_f16 v[32:35], v[178:181], v[194:197], v[32:35]
	v_mfma_f32_16x16x32_f16 v[20:23], v[170:173], v[202:205], v[20:23]
	v_mfma_f32_16x16x32_f16 v[16:19], v[178:181], v[202:205], v[16:19]
	v_mfma_f32_16x16x32_f16 v[4:7], v[170:173], v[210:213], v[4:7]
	v_mfma_f32_16x16x32_f16 v[0:3], v[178:181], v[210:213], v[0:3]
	s_barrier
	s_add_i32 s46, 0, 0x18000
	v_add_u32_e32 v149, s46, v147
	s_add_i32 s47, 0, 0x1c000
	ds_read_b128 v[150:153], v149
	ds_read_b128 v[154:157], v149 offset:1024
	ds_read_b128 v[158:161], v149 offset:2048
	ds_read_b128 v[162:165], v149 offset:3072
	v_add_u32_e32 v149, s47, v147
	ds_read_b128 v[166:169], v149
	ds_read_b128 v[170:173], v149 offset:1024
	ds_read_b128 v[174:177], v149 offset:2048
	ds_read_b128 v[178:181], v149 offset:3072
	s_add_u32 s30, s30, 0x40000
	s_addc_u32 s31, s31, 0
	s_mov_b32 m0, s37
	v_lshl_add_u64 v[222:223], s[30:31], 0, v[130:131]
	ds_read_b128 v[182:185], v148 offset:32768
	ds_read_b128 v[186:189], v148 offset:33792
	ds_read_b128 v[190:193], v148 offset:34816
	ds_read_b128 v[194:197], v148 offset:35840
	ds_read_b128 v[198:201], v148 offset:36864
	ds_read_b128 v[202:205], v148 offset:37888
	ds_read_b128 v[206:209], v148 offset:38912
	ds_read_b128 v[210:213], v148 offset:39936
	global_load_lds_dwordx4 v[222:223], off sc1
	v_lshl_add_u64 v[222:223], s[30:31], 0, v[132:133]
	s_mov_b32 m0, s38
	s_nop 0
	global_load_lds_dwordx4 v[222:223], off sc1
	s_waitcnt vmcnt(8)
	s_waitcnt lgkmcnt(0)
	s_barrier
	s_waitcnt lgkmcnt(0)
	v_mfma_f32_16x16x32_f16 v[124:127], v[150:153], v[182:185], v[124:127]
	v_mfma_f32_16x16x32_f16 v[120:123], v[158:161], v[182:185], v[120:123]
	v_mfma_f32_16x16x32_f16 v[108:111], v[150:153], v[190:193], v[108:111]
	v_mfma_f32_16x16x32_f16 v[104:107], v[158:161], v[190:193], v[104:107]
	v_mfma_f32_16x16x32_f16 v[92:95], v[150:153], v[198:201], v[92:95]
	v_mfma_f32_16x16x32_f16 v[88:91], v[158:161], v[198:201], v[88:91]
	v_mfma_f32_16x16x32_f16 v[76:79], v[150:153], v[206:209], v[76:79]
	v_mfma_f32_16x16x32_f16 v[72:75], v[158:161], v[206:209], v[72:75]
	v_mfma_f32_16x16x32_f16 v[124:127], v[154:157], v[186:189], v[124:127]
	v_mfma_f32_16x16x32_f16 v[120:123], v[162:165], v[186:189], v[120:123]
	v_mfma_f32_16x16x32_f16 v[108:111], v[154:157], v[194:197], v[108:111]
	v_mfma_f32_16x16x32_f16 v[104:107], v[162:165], v[194:197], v[104:107]
	v_mfma_f32_16x16x32_f16 v[92:95], v[154:157], v[202:205], v[92:95]
	v_mfma_f32_16x16x32_f16 v[88:91], v[162:165], v[202:205], v[88:91]
	v_mfma_f32_16x16x32_f16 v[76:79], v[154:157], v[210:213], v[76:79]
	v_mfma_f32_16x16x32_f16 v[72:75], v[162:165], v[210:213], v[72:75]
	v_mfma_f32_16x16x32_f16 v[116:119], v[166:169], v[182:185], v[116:119]
	v_mfma_f32_16x16x32_f16 v[112:115], v[174:177], v[182:185], v[112:115]
	v_mfma_f32_16x16x32_f16 v[100:103], v[166:169], v[190:193], v[100:103]
	v_mfma_f32_16x16x32_f16 v[96:99], v[174:177], v[190:193], v[96:99]
	v_mfma_f32_16x16x32_f16 v[84:87], v[166:169], v[198:201], v[84:87]
	v_mfma_f32_16x16x32_f16 v[80:83], v[174:177], v[198:201], v[80:83]
	v_mfma_f32_16x16x32_f16 v[68:71], v[166:169], v[206:209], v[68:71]
	v_mfma_f32_16x16x32_f16 v[64:67], v[174:177], v[206:209], v[64:67]
	v_mfma_f32_16x16x32_f16 v[116:119], v[170:173], v[186:189], v[116:119]
	v_mfma_f32_16x16x32_f16 v[112:115], v[178:181], v[186:189], v[112:115]
	v_mfma_f32_16x16x32_f16 v[100:103], v[170:173], v[194:197], v[100:103]
	v_mfma_f32_16x16x32_f16 v[96:99], v[178:181], v[194:197], v[96:99]
	v_mfma_f32_16x16x32_f16 v[84:87], v[170:173], v[202:205], v[84:87]
	v_mfma_f32_16x16x32_f16 v[80:83], v[178:181], v[202:205], v[80:83]
	v_mfma_f32_16x16x32_f16 v[68:71], v[170:173], v[210:213], v[68:71]
	v_mfma_f32_16x16x32_f16 v[64:67], v[178:181], v[210:213], v[64:67]
	s_barrier
	s_add_i32 s30, s46, s53
	v_lshl_add_u64 v[214:215], v[214:215], 0, s[20:21]
	s_mov_b32 m0, s30
	ds_read_b128 v[182:185], v148 offset:49152
	ds_read_b128 v[186:189], v148 offset:50176
	ds_read_b128 v[190:193], v148 offset:51200
	ds_read_b128 v[194:197], v148 offset:52224
	ds_read_b128 v[198:201], v148 offset:53248
	ds_read_b128 v[202:205], v148 offset:54272
	ds_read_b128 v[206:209], v148 offset:55296
	ds_read_b128 v[210:213], v148 offset:56320
	global_load_lds_dwordx4 v[214:215], off
	s_add_i32 m0, s30, 0x2000
	s_add_u32 s28, s28, 0x40080
	v_lshl_add_u64 v[214:215], v[216:217], 0, s[20:21]
	s_addc_u32 s29, s29, 0
	s_add_i32 s30, s47, s53
	global_load_lds_dwordx4 v[214:215], off
	v_lshl_add_u64 v[214:215], s[28:29], 0, v[128:129]
	s_mov_b32 m0, s30
	s_nop 0
	global_load_lds_dwordx4 v[214:215], off
	v_lshl_add_u64 v[214:215], s[28:29], 0, v[134:135]
	s_add_i32 m0, s30, 0x2000
	s_nop 0
	global_load_lds_dwordx4 v[214:215], off
	v_lshl_add_u64 v[214:215], v[218:219], 0, s[20:21]
	s_mov_b32 m0, s39
	s_nop 0
	global_load_lds_dwordx4 v[214:215], off sc1
	v_lshl_add_u64 v[214:215], v[220:221], 0, s[20:21]
	s_mov_b32 m0, s40
	s_nop 0
	global_load_lds_dwordx4 v[214:215], off sc1
	s_waitcnt vmcnt(8)
	s_waitcnt lgkmcnt(0)
	s_barrier
	s_waitcnt lgkmcnt(0)
	v_mfma_f32_16x16x32_f16 v[60:63], v[150:153], v[182:185], v[60:63]
	v_mfma_f32_16x16x32_f16 v[56:59], v[158:161], v[182:185], v[56:59]
	v_mfma_f32_16x16x32_f16 v[44:47], v[150:153], v[190:193], v[44:47]
	v_mfma_f32_16x16x32_f16 v[40:43], v[158:161], v[190:193], v[40:43]
	v_mfma_f32_16x16x32_f16 v[28:31], v[150:153], v[198:201], v[28:31]
	v_mfma_f32_16x16x32_f16 v[24:27], v[158:161], v[198:201], v[24:27]
	v_mfma_f32_16x16x32_f16 v[12:15], v[150:153], v[206:209], v[12:15]
	v_mfma_f32_16x16x32_f16 v[8:11], v[158:161], v[206:209], v[8:11]
	v_mfma_f32_16x16x32_f16 v[60:63], v[154:157], v[186:189], v[60:63]
	v_mfma_f32_16x16x32_f16 v[56:59], v[162:165], v[186:189], v[56:59]
	v_mfma_f32_16x16x32_f16 v[44:47], v[154:157], v[194:197], v[44:47]
	v_mfma_f32_16x16x32_f16 v[40:43], v[162:165], v[194:197], v[40:43]
	v_mfma_f32_16x16x32_f16 v[28:31], v[154:157], v[202:205], v[28:31]
	v_mfma_f32_16x16x32_f16 v[24:27], v[162:165], v[202:205], v[24:27]
	v_mfma_f32_16x16x32_f16 v[12:15], v[154:157], v[210:213], v[12:15]
	v_mfma_f32_16x16x32_f16 v[8:11], v[162:165], v[210:213], v[8:11]
	v_mfma_f32_16x16x32_f16 v[52:55], v[166:169], v[182:185], v[52:55]
	v_mfma_f32_16x16x32_f16 v[48:51], v[174:177], v[182:185], v[48:51]
	v_mfma_f32_16x16x32_f16 v[36:39], v[166:169], v[190:193], v[36:39]
	v_mfma_f32_16x16x32_f16 v[32:35], v[174:177], v[190:193], v[32:35]
	v_mfma_f32_16x16x32_f16 v[20:23], v[166:169], v[198:201], v[20:23]
	v_mfma_f32_16x16x32_f16 v[16:19], v[174:177], v[198:201], v[16:19]
	v_mfma_f32_16x16x32_f16 v[4:7], v[166:169], v[206:209], v[4:7]
	v_mfma_f32_16x16x32_f16 v[0:3], v[174:177], v[206:209], v[0:3]
	v_mfma_f32_16x16x32_f16 v[52:55], v[170:173], v[186:189], v[52:55]
	v_mfma_f32_16x16x32_f16 v[48:51], v[178:181], v[186:189], v[48:51]
	v_mfma_f32_16x16x32_f16 v[36:39], v[170:173], v[194:197], v[36:39]
	v_mfma_f32_16x16x32_f16 v[32:35], v[178:181], v[194:197], v[32:35]
	v_mfma_f32_16x16x32_f16 v[20:23], v[170:173], v[202:205], v[20:23]
	v_mfma_f32_16x16x32_f16 v[16:19], v[178:181], v[202:205], v[16:19]
	v_mfma_f32_16x16x32_f16 v[4:7], v[170:173], v[210:213], v[4:7]
	v_mfma_f32_16x16x32_f16 v[0:3], v[178:181], v[210:213], v[0:3]
	s_barrier
	s_add_i32 s45, s45, 2
	s_add_u32 s26, s26, 0x100
	s_addc_u32 s27, s27, 0
	s_cmp_gt_u32 s45, 13
.LBB0_1329:
	s_add_u32 s28, s41, s26
	s_addc_u32 s29, s42, s27
	s_add_u32 s28, s28, 0x7a00100
	s_addc_u32 s29, s29, 0
	s_add_u32 s46, s43, s26
	s_addc_u32 s47, s44, s27
	s_add_i32 s48, 0, 0x10000
	s_cmpk_eq_i32 s26, 0x700
	s_cselect_b32 s31, s25, s29
	s_cselect_b32 s30, s24, s28
	v_add_u32_e32 v149, s48, v147
	s_cselect_b32 s29, s1, s47
	s_cselect_b32 s28, s0, s46
	s_add_i32 s49, 0, 0x14000
	ds_read_b128 v[150:153], v149
	ds_read_b128 v[154:157], v149 offset:1024
	ds_read_b128 v[158:161], v149 offset:2048
	ds_read_b128 v[162:165], v149 offset:3072
	v_add_u32_e32 v149, s49, v147
	ds_read_b128 v[166:169], v149
	ds_read_b128 v[170:173], v149 offset:1024
	ds_read_b128 v[174:177], v149 offset:2048
	ds_read_b128 v[178:181], v149 offset:3072
	v_lshl_add_u64 v[214:215], v[136:137], 0, s[26:27]
	s_add_i32 m0, s35, 0xc000
	ds_read_b128 v[182:185], v148
	ds_read_b128 v[186:189], v148 offset:1024
	ds_read_b128 v[190:193], v148 offset:2048
	ds_read_b128 v[194:197], v148 offset:3072
	ds_read_b128 v[198:201], v148 offset:4096
	ds_read_b128 v[202:205], v148 offset:5120
	ds_read_b128 v[206:209], v148 offset:6144
	ds_read_b128 v[210:213], v148 offset:7168
	global_load_lds_dwordx4 v[214:215], off sc1
	v_lshl_add_u64 v[214:215], v[138:139], 0, s[26:27]
	s_add_i32 m0, s35, 0xe000
	s_nop 0
	global_load_lds_dwordx4 v[214:215], off sc1
	s_waitcnt vmcnt(8)
	s_waitcnt lgkmcnt(0)
	s_barrier
	s_waitcnt lgkmcnt(0)
	v_mfma_f32_16x16x32_f16 v[124:127], v[150:153], v[182:185], v[124:127]
	v_mfma_f32_16x16x32_f16 v[120:123], v[158:161], v[182:185], v[120:123]
	v_mfma_f32_16x16x32_f16 v[108:111], v[150:153], v[190:193], v[108:111]
	v_mfma_f32_16x16x32_f16 v[104:107], v[158:161], v[190:193], v[104:107]
	v_mfma_f32_16x16x32_f16 v[92:95], v[150:153], v[198:201], v[92:95]
	v_mfma_f32_16x16x32_f16 v[88:91], v[158:161], v[198:201], v[88:91]
	v_mfma_f32_16x16x32_f16 v[76:79], v[150:153], v[206:209], v[76:79]
	v_mfma_f32_16x16x32_f16 v[72:75], v[158:161], v[206:209], v[72:75]
	v_mfma_f32_16x16x32_f16 v[124:127], v[154:157], v[186:189], v[124:127]
	v_mfma_f32_16x16x32_f16 v[120:123], v[162:165], v[186:189], v[120:123]
	v_mfma_f32_16x16x32_f16 v[108:111], v[154:157], v[194:197], v[108:111]
	v_mfma_f32_16x16x32_f16 v[104:107], v[162:165], v[194:197], v[104:107]
	v_mfma_f32_16x16x32_f16 v[92:95], v[154:157], v[202:205], v[92:95]
	v_mfma_f32_16x16x32_f16 v[88:91], v[162:165], v[202:205], v[88:91]
	v_mfma_f32_16x16x32_f16 v[76:79], v[154:157], v[210:213], v[76:79]
	v_mfma_f32_16x16x32_f16 v[72:75], v[162:165], v[210:213], v[72:75]
	v_mfma_f32_16x16x32_f16 v[116:119], v[166:169], v[182:185], v[116:119]
	v_mfma_f32_16x16x32_f16 v[112:115], v[174:177], v[182:185], v[112:115]
	v_mfma_f32_16x16x32_f16 v[100:103], v[166:169], v[190:193], v[100:103]
	v_mfma_f32_16x16x32_f16 v[96:99], v[174:177], v[190:193], v[96:99]
	v_mfma_f32_16x16x32_f16 v[84:87], v[166:169], v[198:201], v[84:87]
	v_mfma_f32_16x16x32_f16 v[80:83], v[174:177], v[198:201], v[80:83]
	v_mfma_f32_16x16x32_f16 v[68:71], v[166:169], v[206:209], v[68:71]
	v_mfma_f32_16x16x32_f16 v[64:67], v[174:177], v[206:209], v[64:67]
	v_mfma_f32_16x16x32_f16 v[116:119], v[170:173], v[186:189], v[116:119]
	v_mfma_f32_16x16x32_f16 v[112:115], v[178:181], v[186:189], v[112:115]
	v_mfma_f32_16x16x32_f16 v[100:103], v[170:173], v[194:197], v[100:103]
	v_mfma_f32_16x16x32_f16 v[96:99], v[178:181], v[194:197], v[96:99]
	v_mfma_f32_16x16x32_f16 v[84:87], v[170:173], v[202:205], v[84:87]
	v_mfma_f32_16x16x32_f16 v[80:83], v[178:181], v[202:205], v[80:83]
	v_mfma_f32_16x16x32_f16 v[68:71], v[170:173], v[210:213], v[68:71]
	v_mfma_f32_16x16x32_f16 v[64:67], v[178:181], v[210:213], v[64:67]
	s_barrier
	s_add_i32 s46, s48, s53
	v_lshl_add_u64 v[214:215], s[28:29], 0, v[128:129]
	s_mov_b32 m0, s46
	ds_read_b128 v[182:185], v148 offset:16384
	ds_read_b128 v[186:189], v148 offset:17408
	ds_read_b128 v[190:193], v148 offset:18432
	ds_read_b128 v[194:197], v148 offset:19456
	ds_read_b128 v[198:201], v148 offset:20480
	ds_read_b128 v[202:205], v148 offset:21504
	ds_read_b128 v[206:209], v148 offset:22528
	ds_read_b128 v[210:213], v148 offset:23552
	global_load_lds_dwordx4 v[214:215], off
	s_add_i32 m0, s46, 0x2000
	s_add_u32 s46, s28, 0x40000
	v_lshl_add_u64 v[216:217], s[28:29], 0, v[134:135]
	s_addc_u32 s47, s29, 0
	s_add_i32 s48, s49, s53
	global_load_lds_dwordx4 v[216:217], off
	v_lshl_add_u64 v[218:219], s[46:47], 0, v[128:129]
	s_mov_b32 m0, s48
	v_lshl_add_u64 v[220:221], s[30:31], 0, v[132:133]
	global_load_lds_dwordx4 v[218:219], off
	v_lshl_add_u64 v[218:219], s[46:47], 0, v[134:135]
	s_add_i32 m0, s48, 0x2000
	s_nop 0
	global_load_lds_dwordx4 v[218:219], off
	v_lshl_add_u64 v[218:219], s[30:31], 0, v[130:131]
	s_mov_b32 m0, s35
	s_nop 0
	global_load_lds_dwordx4 v[218:219], off sc1
	s_mov_b32 m0, s36
	s_nop 0
	global_load_lds_dwordx4 v[220:221], off sc1
	s_waitcnt vmcnt(8)
	s_waitcnt lgkmcnt(0)
	s_barrier
	s_waitcnt lgkmcnt(0)
	v_mfma_f32_16x16x32_f16 v[60:63], v[150:153], v[182:185], v[60:63]
	v_mfma_f32_16x16x32_f16 v[56:59], v[158:161], v[182:185], v[56:59]
	v_mfma_f32_16x16x32_f16 v[44:47], v[150:153], v[190:193], v[44:47]
	v_mfma_f32_16x16x32_f16 v[40:43], v[158:161], v[190:193], v[40:43]
	v_mfma_f32_16x16x32_f16 v[28:31], v[150:153], v[198:201], v[28:31]
	v_mfma_f32_16x16x32_f16 v[24:27], v[158:161], v[198:201], v[24:27]
	v_mfma_f32_16x16x32_f16 v[12:15], v[150:153], v[206:209], v[12:15]
	v_mfma_f32_16x16x32_f16 v[8:11], v[158:161], v[206:209], v[8:11]
	v_mfma_f32_16x16x32_f16 v[60:63], v[154:157], v[186:189], v[60:63]
	v_mfma_f32_16x16x32_f16 v[56:59], v[162:165], v[186:189], v[56:59]
	v_mfma_f32_16x16x32_f16 v[44:47], v[154:157], v[194:197], v[44:47]
	v_mfma_f32_16x16x32_f16 v[40:43], v[162:165], v[194:197], v[40:43]
	v_mfma_f32_16x16x32_f16 v[28:31], v[154:157], v[202:205], v[28:31]
	v_mfma_f32_16x16x32_f16 v[24:27], v[162:165], v[202:205], v[24:27]
	v_mfma_f32_16x16x32_f16 v[12:15], v[154:157], v[210:213], v[12:15]
	v_mfma_f32_16x16x32_f16 v[8:11], v[162:165], v[210:213], v[8:11]
	v_mfma_f32_16x16x32_f16 v[52:55], v[166:169], v[182:185], v[52:55]
	v_mfma_f32_16x16x32_f16 v[48:51], v[174:177], v[182:185], v[48:51]
	v_mfma_f32_16x16x32_f16 v[36:39], v[166:169], v[190:193], v[36:39]
	v_mfma_f32_16x16x32_f16 v[32:35], v[174:177], v[190:193], v[32:35]
	v_mfma_f32_16x16x32_f16 v[20:23], v[166:169], v[198:201], v[20:23]
	v_mfma_f32_16x16x32_f16 v[16:19], v[174:177], v[198:201], v[16:19]
	v_mfma_f32_16x16x32_f16 v[4:7], v[166:169], v[206:209], v[4:7]
	v_mfma_f32_16x16x32_f16 v[0:3], v[174:177], v[206:209], v[0:3]
	v_mfma_f32_16x16x32_f16 v[52:55], v[170:173], v[186:189], v[52:55]
	v_mfma_f32_16x16x32_f16 v[48:51], v[178:181], v[186:189], v[48:51]
	v_mfma_f32_16x16x32_f16 v[36:39], v[170:173], v[194:197], v[36:39]
	v_mfma_f32_16x16x32_f16 v[32:35], v[178:181], v[194:197], v[32:35]
	v_mfma_f32_16x16x32_f16 v[20:23], v[170:173], v[202:205], v[20:23]
	v_mfma_f32_16x16x32_f16 v[16:19], v[178:181], v[202:205], v[16:19]
	v_mfma_f32_16x16x32_f16 v[4:7], v[170:173], v[210:213], v[4:7]
	v_mfma_f32_16x16x32_f16 v[0:3], v[178:181], v[210:213], v[0:3]
	s_barrier
	s_add_i32 s46, 0, 0x18000
	v_add_u32_e32 v149, s46, v147
	s_add_i32 s47, 0, 0x1c000
	ds_read_b128 v[150:153], v149
	ds_read_b128 v[154:157], v149 offset:1024
	ds_read_b128 v[158:161], v149 offset:2048
	ds_read_b128 v[162:165], v149 offset:3072
	v_add_u32_e32 v149, s47, v147
	ds_read_b128 v[166:169], v149
	ds_read_b128 v[170:173], v149 offset:1024
	ds_read_b128 v[174:177], v149 offset:2048
	ds_read_b128 v[178:181], v149 offset:3072
	s_add_u32 s30, s30, 0x40000
	s_addc_u32 s31, s31, 0
	s_mov_b32 m0, s37
	v_lshl_add_u64 v[222:223], s[30:31], 0, v[130:131]
	ds_read_b128 v[182:185], v148 offset:32768
	ds_read_b128 v[186:189], v148 offset:33792
	ds_read_b128 v[190:193], v148 offset:34816
	ds_read_b128 v[194:197], v148 offset:35840
	ds_read_b128 v[198:201], v148 offset:36864
	ds_read_b128 v[202:205], v148 offset:37888
	ds_read_b128 v[206:209], v148 offset:38912
	ds_read_b128 v[210:213], v148 offset:39936
	global_load_lds_dwordx4 v[222:223], off sc1
	v_lshl_add_u64 v[222:223], s[30:31], 0, v[132:133]
	s_mov_b32 m0, s38
	s_nop 0
	global_load_lds_dwordx4 v[222:223], off sc1
	s_waitcnt vmcnt(8)
	s_waitcnt lgkmcnt(0)
	s_barrier
	s_waitcnt lgkmcnt(0)
	v_mfma_f32_16x16x32_f16 v[124:127], v[150:153], v[182:185], v[124:127]
	v_mfma_f32_16x16x32_f16 v[120:123], v[158:161], v[182:185], v[120:123]
	v_mfma_f32_16x16x32_f16 v[108:111], v[150:153], v[190:193], v[108:111]
	v_mfma_f32_16x16x32_f16 v[104:107], v[158:161], v[190:193], v[104:107]
	v_mfma_f32_16x16x32_f16 v[92:95], v[150:153], v[198:201], v[92:95]
	v_mfma_f32_16x16x32_f16 v[88:91], v[158:161], v[198:201], v[88:91]
	v_mfma_f32_16x16x32_f16 v[76:79], v[150:153], v[206:209], v[76:79]
	v_mfma_f32_16x16x32_f16 v[72:75], v[158:161], v[206:209], v[72:75]
	v_mfma_f32_16x16x32_f16 v[124:127], v[154:157], v[186:189], v[124:127]
	v_mfma_f32_16x16x32_f16 v[120:123], v[162:165], v[186:189], v[120:123]
	v_mfma_f32_16x16x32_f16 v[108:111], v[154:157], v[194:197], v[108:111]
	v_mfma_f32_16x16x32_f16 v[104:107], v[162:165], v[194:197], v[104:107]
	v_mfma_f32_16x16x32_f16 v[92:95], v[154:157], v[202:205], v[92:95]
	v_mfma_f32_16x16x32_f16 v[88:91], v[162:165], v[202:205], v[88:91]
	v_mfma_f32_16x16x32_f16 v[76:79], v[154:157], v[210:213], v[76:79]
	v_mfma_f32_16x16x32_f16 v[72:75], v[162:165], v[210:213], v[72:75]
	v_mfma_f32_16x16x32_f16 v[116:119], v[166:169], v[182:185], v[116:119]
	v_mfma_f32_16x16x32_f16 v[112:115], v[174:177], v[182:185], v[112:115]
	v_mfma_f32_16x16x32_f16 v[100:103], v[166:169], v[190:193], v[100:103]
	v_mfma_f32_16x16x32_f16 v[96:99], v[174:177], v[190:193], v[96:99]
	v_mfma_f32_16x16x32_f16 v[84:87], v[166:169], v[198:201], v[84:87]
	v_mfma_f32_16x16x32_f16 v[80:83], v[174:177], v[198:201], v[80:83]
	v_mfma_f32_16x16x32_f16 v[68:71], v[166:169], v[206:209], v[68:71]
	v_mfma_f32_16x16x32_f16 v[64:67], v[174:177], v[206:209], v[64:67]
	v_mfma_f32_16x16x32_f16 v[116:119], v[170:173], v[186:189], v[116:119]
	v_mfma_f32_16x16x32_f16 v[112:115], v[178:181], v[186:189], v[112:115]
	v_mfma_f32_16x16x32_f16 v[100:103], v[170:173], v[194:197], v[100:103]
	v_mfma_f32_16x16x32_f16 v[96:99], v[178:181], v[194:197], v[96:99]
	v_mfma_f32_16x16x32_f16 v[84:87], v[170:173], v[202:205], v[84:87]
	v_mfma_f32_16x16x32_f16 v[80:83], v[178:181], v[202:205], v[80:83]
	v_mfma_f32_16x16x32_f16 v[68:71], v[170:173], v[210:213], v[68:71]
	v_mfma_f32_16x16x32_f16 v[64:67], v[178:181], v[210:213], v[64:67]
	s_barrier
	s_add_i32 s30, s46, s53
	v_lshl_add_u64 v[214:215], v[214:215], 0, s[20:21]
	s_mov_b32 m0, s30
	ds_read_b128 v[182:185], v148 offset:49152
	ds_read_b128 v[186:189], v148 offset:50176
	ds_read_b128 v[190:193], v148 offset:51200
	ds_read_b128 v[194:197], v148 offset:52224
	ds_read_b128 v[198:201], v148 offset:53248
	ds_read_b128 v[202:205], v148 offset:54272
	ds_read_b128 v[206:209], v148 offset:55296
	ds_read_b128 v[210:213], v148 offset:56320
	global_load_lds_dwordx4 v[214:215], off
	s_add_i32 m0, s30, 0x2000
	s_add_u32 s28, s28, 0x40080
	v_lshl_add_u64 v[214:215], v[216:217], 0, s[20:21]
	s_addc_u32 s29, s29, 0
	s_add_i32 s30, s47, s53
	global_load_lds_dwordx4 v[214:215], off
	v_lshl_add_u64 v[214:215], s[28:29], 0, v[128:129]
	s_mov_b32 m0, s30
	s_nop 0
	global_load_lds_dwordx4 v[214:215], off
	v_lshl_add_u64 v[214:215], s[28:29], 0, v[134:135]
	s_add_i32 m0, s30, 0x2000
	s_nop 0
	global_load_lds_dwordx4 v[214:215], off
	v_lshl_add_u64 v[214:215], v[218:219], 0, s[20:21]
	s_mov_b32 m0, s39
	s_nop 0
	global_load_lds_dwordx4 v[214:215], off sc1
	v_lshl_add_u64 v[214:215], v[220:221], 0, s[20:21]
	s_mov_b32 m0, s40
	s_nop 0
	global_load_lds_dwordx4 v[214:215], off sc1
	s_waitcnt vmcnt(8)
	s_waitcnt lgkmcnt(0)
	s_barrier
	s_waitcnt lgkmcnt(0)
	v_mfma_f32_16x16x32_f16 v[60:63], v[150:153], v[182:185], v[60:63]
	v_mfma_f32_16x16x32_f16 v[56:59], v[158:161], v[182:185], v[56:59]
	v_mfma_f32_16x16x32_f16 v[44:47], v[150:153], v[190:193], v[44:47]
	v_mfma_f32_16x16x32_f16 v[40:43], v[158:161], v[190:193], v[40:43]
	v_mfma_f32_16x16x32_f16 v[28:31], v[150:153], v[198:201], v[28:31]
	v_mfma_f32_16x16x32_f16 v[24:27], v[158:161], v[198:201], v[24:27]
	v_mfma_f32_16x16x32_f16 v[12:15], v[150:153], v[206:209], v[12:15]
	v_mfma_f32_16x16x32_f16 v[8:11], v[158:161], v[206:209], v[8:11]
	v_mfma_f32_16x16x32_f16 v[60:63], v[154:157], v[186:189], v[60:63]
	v_mfma_f32_16x16x32_f16 v[56:59], v[162:165], v[186:189], v[56:59]
	v_mfma_f32_16x16x32_f16 v[44:47], v[154:157], v[194:197], v[44:47]
	v_mfma_f32_16x16x32_f16 v[40:43], v[162:165], v[194:197], v[40:43]
	v_mfma_f32_16x16x32_f16 v[28:31], v[154:157], v[202:205], v[28:31]
	v_mfma_f32_16x16x32_f16 v[24:27], v[162:165], v[202:205], v[24:27]
	v_mfma_f32_16x16x32_f16 v[12:15], v[154:157], v[210:213], v[12:15]
	v_mfma_f32_16x16x32_f16 v[8:11], v[162:165], v[210:213], v[8:11]
	v_mfma_f32_16x16x32_f16 v[52:55], v[166:169], v[182:185], v[52:55]
	v_mfma_f32_16x16x32_f16 v[48:51], v[174:177], v[182:185], v[48:51]
	v_mfma_f32_16x16x32_f16 v[36:39], v[166:169], v[190:193], v[36:39]
	v_mfma_f32_16x16x32_f16 v[32:35], v[174:177], v[190:193], v[32:35]
	v_mfma_f32_16x16x32_f16 v[20:23], v[166:169], v[198:201], v[20:23]
	v_mfma_f32_16x16x32_f16 v[16:19], v[174:177], v[198:201], v[16:19]
	v_mfma_f32_16x16x32_f16 v[4:7], v[166:169], v[206:209], v[4:7]
	v_mfma_f32_16x16x32_f16 v[0:3], v[174:177], v[206:209], v[0:3]
	v_mfma_f32_16x16x32_f16 v[52:55], v[170:173], v[186:189], v[52:55]
	v_mfma_f32_16x16x32_f16 v[48:51], v[178:181], v[186:189], v[48:51]
	v_mfma_f32_16x16x32_f16 v[36:39], v[170:173], v[194:197], v[36:39]
	v_mfma_f32_16x16x32_f16 v[32:35], v[178:181], v[194:197], v[32:35]
	v_mfma_f32_16x16x32_f16 v[20:23], v[170:173], v[202:205], v[20:23]
	v_mfma_f32_16x16x32_f16 v[16:19], v[178:181], v[202:205], v[16:19]
	v_mfma_f32_16x16x32_f16 v[4:7], v[170:173], v[210:213], v[4:7]
	v_mfma_f32_16x16x32_f16 v[0:3], v[178:181], v[210:213], v[0:3]
	s_barrier
	s_add_i32 s45, s45, 2
	s_add_u32 s26, s26, 0x100
	s_addc_u32 s27, s27, 0
	s_cmp_gt_u32 s45, 13
	s_cbranch_scc0 .LBB0_1329
	s_and_b64 vcc, exec, s[16:17]
	s_cbranch_vccz .LBB0_1332
	s_barrier
